# baseline (speedup 1.0000x reference)
; __device__ __forceinline__ float fexp2(float x) { return __builtin_amdgcn_exp2f(x); }
; template <int DKA, int DKB, int DV, bool BAND, bool SINK> ...
;     ...
;         float ls = 0.f;
; #pragma unroll
;         for (int kb2 = 0; kb2 < 2; ++kb2)
; #pragma unroll
;           for (int j = 0; j < 4; ++j) {
;             float pv = fexp2(s[qb][kb2][j] - mx);
;             s[qb][kb2][j] = pv;
;             ls += pv;
;           }
;         lrun[qb] = lrun[qb] * alpha + ls;
;         if (__any(alpha != 1.f)) {
; #pragma unroll
;           for (int eb = 0; eb < EB; ++eb) {
;             o[qb][eb][0] *= alpha; o[qb][eb][1] *= alpha; o[qb][eb][2] *= alpha; o[qb][eb][3] *= alpha;
;           }
;         }
;       }
;       bf16x8 pf[2];
; #pragma unroll
;       for (int qb = 0; qb < 2; ++qb)
;         pf[qb] = mk8(pack2(s[qb][0][0], s[qb][0][1]), pack2(s[qb][0][2], s[qb][0][3]),
;                      pack2(s[qb][1][0], s[qb][1][1]), pack2(s[qb][1][2], s[qb][1][3]));
; #pragma unroll
;       for (int eb = 0; eb < EB; ++eb) {
;         const char* vrow = vbuf + (eb * 16 + fr) * 128 + (fq & 1) * 8;
;         uint2 v0 = *(const uint2*)(vrow + (((kk * 4 + (fq >> 1)) ^ swz8) * 16));
;         uint2 v1 = *(const uint2*)(vrow + (((kk * 4 + 2 + (fq >> 1)) ^ swz8) * 16));
;         bf16x8 vf = mk8(v0.x, v0.y, v1.x, v1.y);
; #pragma unroll
;         for (int qb = 0; qb < 2; ++qb) o[qb][eb] = mfma16(vf, pf[qb], o[qb][eb]);
;       }
;     }
;   }
; #pragma unroll
;   for (int qb = 0; qb < 2; ++qb) {
;     float lt = lrun[qb];
;     lt += __shfl_xor(lt, 16);
;     lt += __shfl_xor(lt, 32);
;     const float inv = 1.f / lt;
; #pragma unroll
;     for (int eb = 0; eb < EB; ++eb) {
;       f32x4 v = o[qb][eb];
;       v[0] *= inv; v[1] *= inv; v[2] *= inv; v[3] *= inv;
;       store4bf(Op + (size_t)(wave * 32 + qb * 16 + fr) * ldo + eb * 16 + fq * 4, v);
;     }
;   }
.LBB0_514:
	v_sub_f32_e32 v37, v40, v5
	v_mul_f32_e32 v38, v67, v0
	v_exp_f32_e32 v67, v37
	v_sub_f32_e32 v19, v19, v5
	v_exp_f32_e32 v69, v19
	v_sub_f32_e32 v19, v36, v5
	v_add_f32_e32 v0, 0, v75
	v_exp_f32_e32 v71, v19
	v_sub_f32_e32 v17, v17, v5
	v_add_f32_e32 v0, v77, v0
	v_exp_f32_e32 v73, v17
	v_sub_f32_e32 v17, v18, v5
	v_sub_f32_e32 v4, v4, v5
	v_exp_f32_e32 v75, v17
	v_sub_f32_e32 v16, v16, v5
	v_exp_f32_e32 v39, v4
	v_sub_f32_e32 v3, v3, v5
	v_pk_add_f32 v[4:5], v[66:67], v[0:1]
	v_exp_f32_e32 v77, v16
	v_pk_add_f32 v[4:5], v[68:69], v[4:5]
	v_exp_f32_e32 v16, v3
	v_pk_add_f32 v[4:5], v[70:71], v[4:5]
	v_sub_f32_e32 v3, v14, v15
	v_pk_add_f32 v[4:5], v[72:73], v[4:5]
	v_add_f32_e32 v0, 0, v81
	v_pk_add_f32 v[4:5], v[74:75], v[4:5]
	v_add_f32_e32 v0, v83, v0
	v_pk_add_f32 v[4:5], v[76:77], v[4:5]
	v_add_u32_e32 v48, v94, v95
	v_pk_add_f32 v[4:5], v[38:39], v[4:5]
	v_cvt_pk_bf16_f32 v39, v39, v16
	v_add_f32_e32 v66, v5, v16
	v_fmac_f32_e32 v66, v4, v2
	v_mul_f32_e32 v2, v79, v64
	v_exp_f32_e32 v79, v3
	v_sub_f32_e32 v3, v12, v15
	v_exp_f32_e32 v81, v3
	v_sub_f32_e32 v3, v13, v15
	v_exp_f32_e32 v83, v3
	v_sub_f32_e32 v3, v10, v15
	v_exp_f32_e32 v85, v3
	v_sub_f32_e32 v3, v11, v15
	v_sub_f32_e32 v4, v7, v15
	v_exp_f32_e32 v87, v3
	v_sub_f32_e32 v3, v8, v15
	v_exp_f32_e32 v7, v4
	v_pk_add_f32 v[4:5], v[78:79], v[0:1]
	v_exp_f32_e32 v89, v3
	v_sub_f32_e32 v3, v9, v15
	v_pk_add_f32 v[4:5], v[80:81], v[4:5]
	v_exp_f32_e32 v3, v3
	v_pk_add_f32 v[4:5], v[82:83], v[4:5]
	v_add_u32_e32 v0, v94, v96
	v_pk_add_f32 v[4:5], v[84:85], v[4:5]
	v_cvt_pk_bf16_f32 v13, v3, v7
	v_pk_add_f32 v[4:5], v[86:87], v[4:5]
	ds_read2st64_b64 v[14:17], v48 offset0:48 offset1:52
	v_pk_add_f32 v[4:5], v[88:89], v[4:5]
	v_cvt_pk_bf16_f32 v10, v79, v81
	v_pk_add_f32 v[4:5], v[2:3], v[4:5]
	v_cvt_pk_bf16_f32 v11, v83, v85
	v_add_f32_e32 v64, v5, v7
	v_fmac_f32_e32 v64, v4, v6
	ds_read2st64_b64 v[2:5], v0 offset0:48 offset1:52
	s_waitcnt lgkmcnt(0)
	v_mov_b32_e32 v8, v14
	v_mov_b32_e32 v9, v15
	v_cvt_pk_bf16_f32 v12, v87, v89
	v_cvt_pk_bf16_f32 v36, v67, v69
	v_mov_b32_e32 v6, v2
	v_mov_b32_e32 v7, v3
	v_mov_b32_e32 v14, v4
	v_mov_b32_e32 v15, v5
	v_cvt_pk_bf16_f32 v37, v71, v73
	v_cvt_pk_bf16_f32 v38, v75, v77
	s_lshl_b64 s[0:1], s[8:9], 11
	v_mfma_f32_16x16x32_bf16 v[40:43], v[6:9], v[10:13], v[44:47]
	s_add_u32 s0, s42, s0
	s_addc_u32 s1, s43, s1
	s_lshl_b32 s6, s12, 1
	v_mfma_f32_16x16x32_bf16 v[44:47], v[14:17], v[10:13], v[56:59]
	s_add_u32 s8, s0, s6
	s_addc_u32 s9, s1, 0
	s_add_i32 s11, s11, s87
	v_mfma_f32_16x16x32_bf16 v[2:5], v[14:17], v[36:39], v[60:63]
	ds_read2st64_b64 v[16:19], v0 offset0:56 offset1:60
	ds_read2st64_b64 v[48:51], v48 offset0:56 offset1:60
	v_lshlrev_b32_e32 v0, 3, v93
	s_add_i32 s10, s10, s86
	v_mfma_f32_16x16x32_bf16 v[6:9], v[6:9], v[36:39], v[52:55]
	s_waitcnt lgkmcnt(0)
	v_mov_b32_e32 v14, v16
	v_mov_b32_e32 v15, v17
	v_mov_b32_e32 v16, v48
	v_mov_b32_e32 v17, v49
	v_mov_b32_e32 v48, v18
	v_mov_b32_e32 v49, v19
	v_lshl_add_u64 v[18:19], s[8:9], 0, v[0:1]
	ds_bpermute_b32 v0, v92, v64
	v_mfma_f32_16x16x32_bf16 v[20:23], v[14:17], v[10:13], v[20:23]
	s_cmpk_lt_i32 s11, 0x100
	s_waitcnt lgkmcnt(0)
	v_add_f32_e32 v0, v64, v0
	v_mfma_f32_16x16x32_bf16 v[14:17], v[14:17], v[36:39], v[24:27]
	v_mfma_f32_16x16x32_bf16 v[24:27], v[48:51], v[10:13], v[28:31]
	s_nop 2
	ds_bpermute_b32 v28, v91, v0
	v_mfma_f32_16x16x32_bf16 v[10:13], v[48:51], v[36:39], v[32:35]
	s_waitcnt lgkmcnt(0)
	v_add_f32_e32 v0, v0, v28
	v_div_scale_f32 v28, s[0:1], v0, v0, 1.0
	v_rcp_f32_e32 v29, v28
	s_nop 0
	v_fma_f32 v30, -v28, v29, 1.0
	v_fmac_f32_e32 v29, v30, v29
	v_div_scale_f32 v30, vcc, 1.0, v0, 1.0
	v_mul_f32_e32 v31, v30, v29
	v_fma_f32 v32, -v28, v31, v30
	v_fmac_f32_e32 v31, v32, v29
	v_fma_f32 v28, -v28, v31, v30
	v_div_fmas_f32 v28, v28, v29, v31
	v_div_fixup_f32 v28, v28, v0, 1.0
	v_lshlrev_b32_e32 v0, 11, v90
	v_lshl_or_b32 v0, v65, 16, v0
	v_lshl_add_u64 v[18:19], v[18:19], 0, v[0:1]
	ds_bpermute_b32 v0, v92, v66
	v_mul_f32_e32 v20, v20, v28
	v_mul_f32_e32 v21, v21, v28
	v_mul_f32_e32 v22, v22, v28
	v_mul_f32_e32 v23, v23, v28
	v_cvt_pk_bf16_f32 v20, v20, v21
	v_cvt_pk_bf16_f32 v21, v22, v23
	global_store_dwordx2 v[18:19], v[20:21], off offset:1088
	v_mul_f32_e32 v20, v24, v28
	v_mul_f32_e32 v21, v25, v28
	v_mul_f32_e32 v22, v26, v28
	v_mul_f32_e32 v23, v27, v28
	v_cvt_pk_bf16_f32 v20, v20, v21
	v_cvt_pk_bf16_f32 v21, v22, v23
	s_waitcnt lgkmcnt(0)
	v_add_f32_e32 v0, v66, v0
	global_store_dwordx2 v[18:19], v[20:21], off offset:1120
	ds_bpermute_b32 v20, v91, v0
	v_mul_f32_e32 v30, v40, v28
	v_mul_f32_e32 v31, v41, v28
	v_mul_f32_e32 v32, v42, v28
	v_mul_f32_e32 v33, v43, v28
	v_cvt_pk_bf16_f32 v30, v30, v31
	v_cvt_pk_bf16_f32 v31, v32, v33
	s_waitcnt lgkmcnt(0)
	v_add_f32_e32 v0, v0, v20
	v_div_scale_f32 v20, s[0:1], v0, v0, 1.0
	v_rcp_f32_e32 v21, v20
	s_mov_b32 s0, 0x8000
	global_store_dwordx2 v[18:19], v[30:31], off offset:1024
	v_mul_f32_e32 v30, v44, v28
	v_mul_f32_e32 v31, v45, v28
	v_fma_f32 v22, -v20, v21, 1.0
	v_fmac_f32_e32 v21, v22, v21
	v_div_scale_f32 v22, vcc, 1.0, v0, 1.0
	v_mul_f32_e32 v23, v22, v21
	v_fma_f32 v24, -v20, v23, v22
	v_fmac_f32_e32 v23, v24, v21
	v_fma_f32 v20, -v20, v23, v22
	v_div_fmas_f32 v20, v20, v21, v23
	v_div_fixup_f32 v0, v20, v0, 1.0
	v_mul_f32_e32 v6, v6, v0
	v_mul_f32_e32 v7, v7, v0
	v_mul_f32_e32 v8, v8, v0
	v_mul_f32_e32 v9, v9, v0
	v_cvt_pk_bf16_f32 v6, v6, v7
	v_cvt_pk_bf16_f32 v7, v8, v9
	v_add_co_u32_e32 v8, vcc, s0, v18
	v_mul_f32_e32 v2, v2, v0
	v_mul_f32_e32 v3, v3, v0
	v_mul_f32_e32 v4, v4, v0
	v_mul_f32_e32 v5, v5, v0
	v_addc_co_u32_e32 v9, vcc, 0, v19, vcc
	v_cvt_pk_bf16_f32 v2, v2, v3
	v_cvt_pk_bf16_f32 v3, v4, v5
	global_store_dwordx2 v[8:9], v[2:3], off offset:1056
	v_mul_f32_e32 v2, v14, v0
	v_mul_f32_e32 v3, v15, v0
	v_mul_f32_e32 v4, v16, v0
	v_mul_f32_e32 v5, v17, v0
	v_cvt_pk_bf16_f32 v2, v2, v3
	v_cvt_pk_bf16_f32 v3, v4, v5
	v_mul_f32_e32 v32, v46, v28
	v_mul_f32_e32 v33, v47, v28
	global_store_dwordx2 v[8:9], v[2:3], off offset:1088
	v_mul_f32_e32 v2, v10, v0
	v_mul_f32_e32 v3, v11, v0
	v_mul_f32_e32 v4, v12, v0
	v_mul_f32_e32 v5, v13, v0
	v_cvt_pk_bf16_f32 v30, v30, v31
	v_cvt_pk_bf16_f32 v31, v32, v33
	v_cvt_pk_bf16_f32 v2, v2, v3
	v_cvt_pk_bf16_f32 v3, v4, v5
	global_store_dwordx2 v[18:19], v[30:31], off offset:1056
	global_store_dwordx2 v[8:9], v[6:7], off offset:1024
	global_store_dwordx2 v[8:9], v[2:3], off offset:1120
	s_cbranch_scc0 .LBB0_513

; __device__ __forceinline__ float fexp2(float x) { return __builtin_amdgcn_exp2f(x); }
; template <int DKA, int DKB, int DV, bool BAND, bool SINK> ...
;     ...
;       for (int kb2 = 0; kb2 < 2; ++kb2) {
;         const int kb = kk * 2 + kb2;
;         bf16x8 kf[KS];
; #pragma unroll
;         for (int ks = 0; ks < KS; ++ks) {
;           if (ks < KSA) {
;             if (DKA == 128) kf[ks] = *(const bf16x8*)(kst + (kb * 16 + fr) * 256 + (((ks * 4 + fq) ^ fr) * 16));
;             else kf[ks] = *(const bf16x8*)(kst + (kb * 16 + fr) * 128 + (((ks * 4 + fq) ^ swz8) * 16));
;           } else {
;             kf[ks] = *(const bf16x8*)(kst + KASZ + (kb * 16 + fr) * 128 + ((((ks - KSA) * 4 + fq) ^ swz8) * 16));
;           }
;         }
; #pragma unroll
;         for (int qb = 0; qb < 2; ++qb) {
;           f32x4 a = (f32x4){0.f, 0.f, 0.f, 0.f};
; #pragma unroll
;           for (int ks = 0; ks < KS; ++ks) a = mfma16(kf[ks], qf[qb][ks], a);
;           s[qb][kb2] = a;
;         }
;       }
; #pragma unroll
;       for (int qb = 0; qb < 2; ++qb) {
;         float mx = mrun[qb];
;         const int qp = qpos0 + wave * 32 + qb * 16 + fr;
; #pragma unroll
;         for (int kb2 = 0; kb2 < 2; ++kb2)
; #pragma unroll
;           for (int j = 0; j < 4; ++j) {
;             float v = s[qb][kb2][j] * scale2;
;             if (BAND && k0 < 2048) {
;               int d = qp - (k0 + (kk * 2 + kb2) * 16 + fq * 4 + j);
;               if (d > 128 || d < -128) v = -1e30f;
;             }
;             s[qb][kb2][j] = v;
;             mx = fmaxf(mx, v);
;           }
;         mx = fmaxf(mx, __shfl_xor(mx, 16));
;         mx = fmaxf(mx, __shfl_xor(mx, 32));
;         const float alpha = fexp2(mrun[qb] - mx);
;         mrun[qb] = mx;
;         float ls = 0.f;
; #pragma unroll
;         for (int kb2 = 0; kb2 < 2; ++kb2)
; #pragma unroll
;           for (int j = 0; j < 4; ++j) {
;             float pv = fexp2(s[qb][kb2][j] - mx);
;             s[qb][kb2][j] = pv;
;             ls += pv;
;           }
;         lrun[qb] = lrun[qb] * alpha + ls;
;         if (__any(alpha != 1.f)) {
; #pragma unroll
;           for (int eb = 0; eb < EB; ++eb) {
;             o[qb][eb][0] *= alpha; o[qb][eb][1] *= alpha; o[qb][eb][2] *= alpha; o[qb][eb][3] *= alpha;
;           }
;         }
.LBB0_517:
	s_and_b32 s6, s0, 0x2000
	v_add_u32_e32 v0, s6, v68
	s_waitcnt vmcnt(0)
	s_waitcnt lgkmcnt(0)
	s_barrier
	v_readfirstlane_b32 s6, v0
	v_add_u32_e32 v0, 0x4000, v0
	s_mov_b32 m0, s6
	v_readfirstlane_b32 s6, v0
	global_load_lds_dwordx4 v[62:63], off
	s_mov_b32 m0, s6
	v_cmp_lt_i32_e32 vcc, v200, v198
	global_load_lds_dwordx4 v[60:61], off
	s_add_i32 s1, s0, 0xffffe000
	v_cndmask_b32_e32 v0, v197, v200, vcc
	v_cmp_lt_i32_e32 vcc, v199, v198
	s_and_b32 s1, s1, 0x2000
	v_lshlrev_b32_e32 v92, 2, v0
	v_cndmask_b32_e32 v0, v197, v199, vcc
	v_lshlrev_b32_e32 v91, 2, v0
	v_or_b32_e32 v0, s1, v70
	v_add_u32_e32 v66, v0, v72
	ds_read_b128 v[52:55], v66
	v_add_u32_e32 v64, v0, v73
	ds_read_b128 v[56:59], v64
	s_waitcnt lgkmcnt(0)
	v_mfma_f32_16x16x32_bf16 v[80:83], v[52:55], v[8:11], 0
	v_mfma_f32_16x16x32_bf16 v[52:55], v[52:55], v[12:15], 0
	v_mfma_f32_16x16x32_bf16 v[80:83], v[56:59], v[4:7], v[80:83]
	v_mfma_f32_16x16x32_bf16 v[52:55], v[56:59], v[16:19], v[52:55]
	ds_read_b128 v[56:59], v66 offset:2048
	ds_read_b128 v[84:87], v64 offset:2048
	s_nop 4
	v_mul_f32_e32 v88, 0x3e38aa3b, v81
	v_mul_f32_e32 v89, 0x3e38aa3b, v82
	s_waitcnt lgkmcnt(0)
	v_mfma_f32_16x16x32_bf16 v[98:101], v[56:59], v[8:11], 0
	v_mul_f32_e32 v97, 0x3e38aa3b, v83
	v_mfma_f32_16x16x32_bf16 v[56:59], v[56:59], v[12:15], 0
	v_mfma_f32_16x16x32_bf16 v[98:101], v[84:87], v[4:7], v[98:101]
	v_mfma_f32_16x16x32_bf16 v[56:59], v[84:87], v[16:19], v[56:59]
	v_mul_f32_e32 v87, 0x3e38aa3b, v80
	v_max3_f32 v0, v74, v87, v88
	v_max3_f32 v0, v0, v89, v97
	s_nop 3
	v_mul_f32_e32 v98, 0x3e38aa3b, v98
	v_mul_f32_e32 v99, 0x3e38aa3b, v99
	v_max3_f32 v0, v0, v98, v99
	v_mul_f32_e32 v100, 0x3e38aa3b, v100
	v_mul_f32_e32 v101, 0x3e38aa3b, v101
	v_max3_f32 v0, v0, v100, v101
	v_mov_b32_e32 v2, v0
	s_waitcnt lgkmcnt(0)
	s_nop 1
	v_permlane16_swap_b32_e32 v0, v2
	v_max_f32_e32 v0, v0, v2
	v_mov_b32_e32 v2, v0
	s_waitcnt lgkmcnt(0)
	v_mov_b32_e32 v85, v0
	s_nop 1
	v_permlane32_swap_b32_e32 v85, v2
	v_max_f32_e32 v85, v85, v2
	v_sub_f32_e32 v0, v74, v85
	v_exp_f32_e32 v2, v0
	s_nop 0
	v_cmp_neq_f32_e32 vcc, 1.0, v2
	s_cbranch_vccz .LBB0_519
	v_mul_f32_e32 v46, v46, v2
	v_mul_f32_e32 v47, v47, v2
	v_mul_f32_e32 v44, v44, v2
	v_mul_f32_e32 v45, v45, v2
	v_mul_f32_e32 v26, v26, v2
	v_mul_f32_e32 v27, v27, v2
	v_mul_f32_e32 v24, v24, v2
	v_mul_f32_e32 v25, v25, v2
	v_mul_f32_e32 v38, v38, v2
	v_mul_f32_e32 v39, v39, v2
	v_mul_f32_e32 v36, v36, v2
	v_mul_f32_e32 v37, v37, v2
	v_mul_f32_e32 v42, v42, v2
	v_mul_f32_e32 v43, v43, v2
	v_mul_f32_e32 v40, v40, v2
	v_mul_f32_e32 v41, v41, v2
.LBB0_519:
	v_mul_f32_e32 v76, 0x3e38aa3b, v52
	v_mul_f32_e32 v74, 0x3e38aa3b, v53
	v_max3_f32 v0, v3, v76, v74
	v_mul_f32_e32 v75, 0x3e38aa3b, v54
	v_mul_f32_e32 v55, 0x3e38aa3b, v55
	v_max3_f32 v0, v0, v75, v55
	v_mul_f32_e32 v56, 0x3e38aa3b, v56
	v_mul_f32_e32 v53, 0x3e38aa3b, v57
	v_max3_f32 v0, v0, v56, v53
	v_mul_f32_e32 v54, 0x3e38aa3b, v58
	v_mul_f32_e32 v52, 0x3e38aa3b, v59
	v_max3_f32 v0, v0, v54, v52
	v_mov_b32_e32 v57, v0
	s_waitcnt lgkmcnt(0)
	s_nop 1
	v_permlane16_swap_b32_e32 v0, v57
	v_max_f32_e32 v0, v0, v57
	v_mov_b32_e32 v57, v0
	s_waitcnt lgkmcnt(0)
	v_mov_b32_e32 v86, v0
	s_nop 1
	v_permlane32_swap_b32_e32 v86, v57
	v_max_f32_e32 v86, v86, v57
	v_sub_f32_e32 v0, v3, v86
	v_exp_f32_e32 v0, v0
	s_nop 0
	v_cmp_neq_f32_e32 vcc, 1.0, v0
	s_cbranch_vccz .LBB0_521
	v_mul_f32_e32 v34, v34, v0
	v_mul_f32_e32 v35, v35, v0
	v_mul_f32_e32 v32, v32, v0
	v_mul_f32_e32 v33, v33, v0
	v_mul_f32_e32 v22, v22, v0
	v_mul_f32_e32 v23, v23, v0
	v_mul_f32_e32 v20, v20, v0
	v_mul_f32_e32 v21, v21, v0
	v_mul_f32_e32 v30, v30, v0
	v_mul_f32_e32 v31, v31, v0
	v_mul_f32_e32 v28, v28, v0
	v_mul_f32_e32 v29, v29, v0
	v_mul_f32_e32 v50, v50, v0
	v_mul_f32_e32 v51, v51, v0
	v_mul_f32_e32 v48, v48, v0
	v_mul_f32_e32 v49, v49, v0
.LBB0_521:
	v_sub_f32_e32 v3, v76, v86
	v_exp_f32_e32 v76, v3
	v_sub_f32_e32 v3, v74, v86
	v_exp_f32_e32 v77, v3
	v_sub_f32_e32 v3, v75, v86
	v_exp_f32_e32 v78, v3
	v_sub_f32_e32 v3, v55, v86
	v_exp_f32_e32 v80, v3
	v_sub_f32_e32 v3, v56, v86
	v_exp_f32_e32 v81, v3
	v_sub_f32_e32 v3, v53, v86
	v_exp_f32_e32 v82, v3
	v_sub_f32_e32 v3, v54, v86
	v_exp_f32_e32 v83, v3
	v_sub_f32_e32 v3, v52, v86
	v_exp_f32_e32 v84, v3
	v_sub_f32_e32 v3, v87, v85
	v_exp_f32_e32 v87, v3
	v_sub_f32_e32 v3, v88, v85
	v_exp_f32_e32 v88, v3
	v_sub_f32_e32 v3, v89, v85
	v_exp_f32_e32 v89, v3
	v_sub_f32_e32 v3, v97, v85
	v_exp_f32_e32 v97, v3
	v_sub_f32_e32 v3, v98, v85
	v_exp_f32_e32 v98, v3
	v_sub_f32_e32 v3, v99, v85
	v_exp_f32_e32 v99, v3
	v_sub_f32_e32 v3, v100, v85
	v_add_u32_e32 v75, s1, v94
	v_exp_f32_e32 v100, v3
	v_sub_f32_e32 v3, v101, v85
	v_exp_f32_e32 v101, v3
	v_add_u32_e32 v3, v75, v71
	v_add_u32_e32 v74, v75, v69
	ds_read2st64_b64 v[102:105], v3 offset0:32 offset1:36
	ds_read2st64_b64 v[106:109], v74 offset0:32 offset1:36
	v_cvt_pk_bf16_f32 v52, v87, v88
	v_cvt_pk_bf16_f32 v53, v89, v97
	v_cvt_pk_bf16_f32 v54, v98, v99
	v_cvt_pk_bf16_f32 v55, v100, v101
	s_waitcnt lgkmcnt(0)
	v_mov_b32_e32 v112, v106
	v_mov_b32_e32 v113, v107
	v_mov_b32_e32 v106, v104
	v_mov_b32_e32 v107, v105
	v_cvt_pk_bf16_f32 v56, v76, v77
	v_cvt_pk_bf16_f32 v57, v78, v80
	v_cvt_pk_bf16_f32 v58, v81, v82
	v_cvt_pk_bf16_f32 v59, v83, v84
	v_mov_b32_e32 v110, v102
	v_mov_b32_e32 v111, v103
	v_mfma_f32_16x16x32_bf16 v[24:27], v[106:109], v[52:55], v[24:27]
	v_mfma_f32_16x16x32_bf16 v[20:23], v[106:109], v[56:59], v[20:23]
	ds_read2st64_b64 v[102:105], v3 offset0:40 offset1:44
	ds_read2st64_b64 v[106:109], v74 offset0:40 offset1:44
	v_mfma_f32_16x16x32_bf16 v[44:47], v[110:113], v[52:55], v[44:47]
	v_mfma_f32_16x16x32_bf16 v[32:35], v[110:113], v[56:59], v[32:35]
	s_waitcnt lgkmcnt(0)
; template <int DKA, int DKB, int DV, bool BAND, bool SINK> ...
;     ...
;       for (int kb2 = 0; kb2 < 2; ++kb2) {
;         const int kb = kk * 2 + kb2;
;         bf16x8 kf[KS];
; #pragma unroll
;         for (int ks = 0; ks < KS; ++ks) {
;           if (ks < KSA) {
;             if (DKA == 128) kf[ks] = *(const bf16x8*)(kst + (kb * 16 + fr) * 256 + (((ks * 4 + fq) ^ fr) * 16));
;             else kf[ks] = *(const bf16x8*)(kst + (kb * 16 + fr) * 128 + (((ks * 4 + fq) ^ swz8) * 16));
;           } else {
;             kf[ks] = *(const bf16x8*)(kst + KASZ + (kb * 16 + fr) * 128 + ((((ks - KSA) * 4 + fq) ^ swz8) * 16));
;           }
;         }
; #pragma unroll
;         for (int qb = 0; qb < 2; ++qb) {
;           f32x4 a = (f32x4){0.f, 0.f, 0.f, 0.f};
; #pragma unroll
;           for (int ks = 0; ks < KS; ++ks) a = mfma16(kf[ks], qf[qb][ks], a);
;           s[qb][kb2] = a;
;         }
;       }
; #pragma unroll
;       for (int qb = 0; qb < 2; ++qb) {
;         float mx = mrun[qb];
;         const int qp = qpos0 + wave * 32 + qb * 16 + fr;
; #pragma unroll
;         for (int kb2 = 0; kb2 < 2; ++kb2)
; #pragma unroll
;           for (int j = 0; j < 4; ++j) {
;             float v = s[qb][kb2][j] * scale2;
;             if (BAND && k0 < 2048) {
;               int d = qp - (k0 + (kk * 2 + kb2) * 16 + fq * 4 + j);
;               if (d > 128 || d < -128) v = -1e30f;
;             }
;             s[qb][kb2][j] = v;
;             mx = fmaxf(mx, v);
;           }
;         mx = fmaxf(mx, __shfl_xor(mx, 16));
;         mx = fmaxf(mx, __shfl_xor(mx, 32));
;         const float alpha = fexp2(mrun[qb] - mx);
;         mrun[qb] = mx;
;         float ls = 0.f;
; #pragma unroll
;         for (int kb2 = 0; kb2 < 2; ++kb2)
; #pragma unroll
;           for (int j = 0; j < 4; ++j) {
;             float pv = fexp2(s[qb][kb2][j] - mx);
;             s[qb][kb2][j] = pv;
;             ls += pv;
;           }
;         lrun[qb] = lrun[qb] * alpha + ls;
;         if (__any(alpha != 1.f)) {
; #pragma unroll
;           for (int eb = 0; eb < EB; ++eb) {
;             o[qb][eb][0] *= alpha; o[qb][eb][1] *= alpha; o[qb][eb][2] *= alpha; o[qb][eb][3] *= alpha;
;           }
;         }
;     ...
;       bf16x8 pf[2];
; #pragma unroll
;       for (int qb = 0; qb < 2; ++qb)
;         pf[qb] = mk8(pack2(s[qb][0][0], s[qb][0][1]), pack2(s[qb][0][2], s[qb][0][3]),
	v_mov_b32_e32 v110, v102
	v_mov_b32_e32 v111, v103
	v_mov_b32_e32 v112, v106
	v_mov_b32_e32 v113, v107
	v_mov_b32_e32 v106, v104
	v_mov_b32_e32 v107, v105
	v_mfma_f32_16x16x32_bf16 v[36:39], v[110:113], v[52:55], v[36:39]
	v_mfma_f32_16x16x32_bf16 v[28:31], v[110:113], v[56:59], v[28:31]
	v_mfma_f32_16x16x32_bf16 v[40:43], v[106:109], v[52:55], v[40:43]
	v_mfma_f32_16x16x32_bf16 v[48:51], v[106:109], v[56:59], v[48:51]
	ds_read_b128 v[52:55], v66 offset:4096
	ds_read_b128 v[56:59], v64 offset:4096
	s_waitcnt lgkmcnt(0)
	v_mfma_f32_16x16x32_bf16 v[102:105], v[52:55], v[8:11], 0
	v_mfma_f32_16x16x32_bf16 v[52:55], v[52:55], v[12:15], 0
	v_mfma_f32_16x16x32_bf16 v[102:105], v[56:59], v[4:7], v[102:105]
	v_mfma_f32_16x16x32_bf16 v[52:55], v[56:59], v[16:19], v[52:55]
	ds_read_b128 v[56:59], v66 offset:6144
	ds_read_b128 v[106:109], v64 offset:6144
	s_waitcnt lgkmcnt(0)
	v_mfma_f32_16x16x32_bf16 v[110:113], v[56:59], v[8:11], 0
	v_mfma_f32_16x16x32_bf16 v[56:59], v[56:59], v[12:15], 0
	v_mfma_f32_16x16x32_bf16 v[110:113], v[106:109], v[4:7], v[110:113]
	v_mfma_f32_16x16x32_bf16 v[56:59], v[106:109], v[16:19], v[56:59]
	v_mul_f32_e32 v109, 0x3e38aa3b, v102
	v_mul_f32_e32 v108, 0x3e38aa3b, v103
	v_max3_f32 v3, v85, v109, v108
	v_mul_f32_e32 v107, 0x3e38aa3b, v104
	v_mul_f32_e32 v106, 0x3e38aa3b, v105
	v_max3_f32 v3, v3, v107, v106
	s_nop 0
	v_mul_f32_e32 v105, 0x3e38aa3b, v110
	v_mul_f32_e32 v104, 0x3e38aa3b, v111
	v_max3_f32 v3, v3, v105, v104
	v_mul_f32_e32 v103, 0x3e38aa3b, v112
	v_mul_f32_e32 v102, 0x3e38aa3b, v113
	v_max3_f32 v3, v3, v103, v102
	v_mov_b32_e32 v64, v3
	s_waitcnt lgkmcnt(0)
	s_nop 1
	v_permlane16_swap_b32_e32 v3, v64
	v_max_f32_e32 v3, v3, v64
	v_mov_b32_e32 v64, v3
	s_waitcnt lgkmcnt(0)
	v_mov_b32_e32 v74, v3
	s_nop 1
	v_permlane32_swap_b32_e32 v74, v64
	v_max_f32_e32 v74, v74, v64
	v_sub_f32_e32 v3, v85, v74
	v_exp_f32_e32 v64, v3
	s_nop 0
	v_cmp_neq_f32_e32 vcc, 1.0, v64
	s_cbranch_vccz .LBB0_523
	v_mul_f32_e32 v46, v46, v64
	v_mul_f32_e32 v47, v47, v64
	v_mul_f32_e32 v44, v44, v64
	v_mul_f32_e32 v45, v45, v64
	v_mul_f32_e32 v26, v26, v64
	v_mul_f32_e32 v27, v27, v64
	v_mul_f32_e32 v24, v24, v64
	v_mul_f32_e32 v25, v25, v64
	v_mul_f32_e32 v38, v38, v64
	v_mul_f32_e32 v39, v39, v64
	v_mul_f32_e32 v36, v36, v64
	v_mul_f32_e32 v37, v37, v64
	v_mul_f32_e32 v42, v42, v64
	v_mul_f32_e32 v43, v43, v64
	v_mul_f32_e32 v40, v40, v64
	v_mul_f32_e32 v41, v41, v64
.LBB0_523:
	v_mul_f32_e32 v3, 0x3e38aa3b, v52
	v_mul_f32_e32 v66, 0x3e38aa3b, v53
	v_max3_f32 v3, v86, v3, v66
	v_mul_f32_e32 v66, 0x3e38aa3b, v54
	v_mul_f32_e32 v85, 0x3e38aa3b, v55
	v_max3_f32 v3, v3, v66, v85
	v_mul_f32_e32 v66, 0x3e38aa3b, v56
	v_mul_f32_e32 v85, 0x3e38aa3b, v57
	v_max3_f32 v3, v3, v66, v85
	v_mul_f32_e32 v66, 0x3e38aa3b, v58
	v_mul_f32_e32 v85, 0x3e38aa3b, v59
	v_max3_f32 v3, v3, v66, v85
	v_mov_b32_e32 v66, v3
	s_waitcnt lgkmcnt(0)
	s_nop 1
	v_permlane16_swap_b32_e32 v3, v66
	v_max_f32_e32 v3, v3, v66
	v_mov_b32_e32 v66, v3
	s_waitcnt lgkmcnt(0)
	s_nop 1
	v_permlane32_swap_b32_e32 v3, v66
	v_max_f32_e32 v3, v3, v66
	v_sub_f32_e32 v66, v86, v3
	v_exp_f32_e32 v66, v66
	s_nop 0
	v_cmp_neq_f32_e32 vcc, 1.0, v66
	s_cbranch_vccz .LBB0_516
	v_mul_f32_e32 v34, v34, v66
	v_mul_f32_e32 v35, v35, v66
	v_mul_f32_e32 v32, v32, v66
	v_mul_f32_e32 v33, v33, v66
	v_mul_f32_e32 v22, v22, v66
	v_mul_f32_e32 v23, v23, v66
	v_mul_f32_e32 v20, v20, v66
	v_mul_f32_e32 v21, v21, v66
	v_mul_f32_e32 v30, v30, v66
	v_mul_f32_e32 v31, v31, v66
	v_mul_f32_e32 v28, v28, v66
	v_mul_f32_e32 v29, v29, v66
	v_mul_f32_e32 v50, v50, v66
	v_mul_f32_e32 v51, v51, v66
	v_mul_f32_e32 v48, v48, v66
	v_mul_f32_e32 v49, v49, v66
	s_branch .LBB0_516
.LBB0_525:
	s_waitcnt vmcnt(0)
	v_add_u32_e32 v2, v70, v73
	v_add_u32_e32 v73, v70, v72
	s_waitcnt lgkmcnt(0)
	s_barrier
	ds_read_b128 v[56:59], v2 offset:10240
	ds_read_b128 v[60:63], v73 offset:10240
	ds_read_b128 v[52:55], v2 offset:8192
	ds_read_b128 v[80:83], v73 offset:8192
	s_waitcnt lgkmcnt(0)
	v_mfma_f32_16x16x32_bf16 v[84:87], v[80:83], v[8:11], 0
	v_mfma_f32_16x16x32_bf16 v[80:83], v[80:83], v[12:15], 0
	v_mfma_f32_16x16x32_bf16 v[84:87], v[52:55], v[4:7], v[84:87]
	v_mfma_f32_16x16x32_bf16 v[52:55], v[52:55], v[16:19], v[80:83]
	v_mfma_f32_16x16x32_bf16 v[80:83], v[60:63], v[8:11], 0
	v_mfma_f32_16x16x32_bf16 v[60:63], v[60:63], v[12:15], 0
	v_mfma_f32_16x16x32_bf16 v[98:101], v[56:59], v[4:7], v[80:83]
	v_mfma_f32_16x16x32_bf16 v[56:59], v[56:59], v[16:19], v[60:63]
	s_nop 5
	v_mul_f32_e32 v61, 0x3e38aa3b, v84
	v_mul_f32_e32 v60, 0x3e38aa3b, v85
	v_max3_f32 v0, v74, v61, v60
	v_mul_f32_e32 v63, 0x3e38aa3b, v86
	v_mul_f32_e32 v62, 0x3e38aa3b, v87
	v_max3_f32 v0, v0, v63, v62
	v_mul_f32_e32 v82, 0x3e38aa3b, v98
	v_mul_f32_e32 v84, 0x3e38aa3b, v99
	v_max3_f32 v0, v0, v82, v84
	v_mul_f32_e32 v86, 0x3e38aa3b, v100
	v_mul_f32_e32 v88, 0x3e38aa3b, v101
	v_max3_f32 v0, v0, v86, v88
	v_mov_b32_e32 v64, v0
	s_waitcnt lgkmcnt(0)
	s_nop 1
	v_permlane16_swap_b32_e32 v0, v64
	v_max_f32_e32 v0, v0, v64
	v_mov_b32_e32 v64, v0
	s_waitcnt lgkmcnt(0)
	v_mov_b32_e32 v85, v0
	s_nop 1
	v_permlane32_swap_b32_e32 v85, v64
	v_max_f32_e32 v85, v85, v64
	v_sub_f32_e32 v0, v74, v85
	v_exp_f32_e32 v64, v0
	s_nop 0
	v_cmp_neq_f32_e32 vcc, 1.0, v64
	s_cbranch_vccz .LBB0_527
	v_mul_f32_e32 v46, v46, v64
	v_mul_f32_e32 v47, v47, v64
	v_mul_f32_e32 v44, v44, v64
	v_mul_f32_e32 v45, v45, v64
	v_mul_f32_e32 v26, v26, v64
	v_mul_f32_e32 v27, v27, v64
	v_mul_f32_e32 v24, v24, v64
	v_mul_f32_e32 v25, v25, v64
	v_mul_f32_e32 v38, v38, v64
	v_mul_f32_e32 v39, v39, v64
	v_mul_f32_e32 v36, v36, v64
	v_mul_f32_e32 v37, v37, v64
	v_mul_f32_e32 v42, v42, v64
	v_mul_f32_e32 v43, v43, v64
	v_mul_f32_e32 v40, v40, v64
	v_mul_f32_e32 v41, v41, v64
; template <int DKA, int DKB, int DV, bool BAND, bool SINK> ...
;     ...
;       for (int kb2 = 0; kb2 < 2; ++kb2) {
;         const int kb = kk * 2 + kb2;
;         bf16x8 kf[KS];
; #pragma unroll
;         for (int ks = 0; ks < KS; ++ks) {
;           if (ks < KSA) {
;             if (DKA == 128) kf[ks] = *(const bf16x8*)(kst + (kb * 16 + fr) * 256 + (((ks * 4 + fq) ^ fr) * 16));
;             else kf[ks] = *(const bf16x8*)(kst + (kb * 16 + fr) * 128 + (((ks * 4 + fq) ^ swz8) * 16));
;           } else {
;             kf[ks] = *(const bf16x8*)(kst + KASZ + (kb * 16 + fr) * 128 + ((((ks - KSA) * 4 + fq) ^ swz8) * 16));
;           }
;         }
; #pragma unroll
;         for (int qb = 0; qb < 2; ++qb) {
;           f32x4 a = (f32x4){0.f, 0.f, 0.f, 0.f};
; #pragma unroll
;           for (int ks = 0; ks < KS; ++ks) a = mfma16(kf[ks], qf[qb][ks], a);
;           s[qb][kb2] = a;
;         }
;       }
; #pragma unroll
;       for (int qb = 0; qb < 2; ++qb) {
;         float mx = mrun[qb];
;         const int qp = qpos0 + wave * 32 + qb * 16 + fr;
; #pragma unroll
;         for (int kb2 = 0; kb2 < 2; ++kb2)
; #pragma unroll
;           for (int j = 0; j < 4; ++j) {
;             float v = s[qb][kb2][j] * scale2;
;             if (BAND && k0 < 2048) {
;               int d = qp - (k0 + (kk * 2 + kb2) * 16 + fq * 4 + j);
;               if (d > 128 || d < -128) v = -1e30f;
;             }
;             s[qb][kb2][j] = v;
;             mx = fmaxf(mx, v);
;           }
;         mx = fmaxf(mx, __shfl_xor(mx, 16));
;         mx = fmaxf(mx, __shfl_xor(mx, 32));
;         const float alpha = fexp2(mrun[qb] - mx);
;         mrun[qb] = mx;
;         float ls = 0.f;
; #pragma unroll
;         for (int kb2 = 0; kb2 < 2; ++kb2)
; #pragma unroll
;           for (int j = 0; j < 4; ++j) {
;             float pv = fexp2(s[qb][kb2][j] - mx);
;             s[qb][kb2][j] = pv;
;             ls += pv;
;           }
;         lrun[qb] = lrun[qb] * alpha + ls;
;         if (__any(alpha != 1.f)) {
; #pragma unroll
;           for (int eb = 0; eb < EB; ++eb) {
;             o[qb][eb][0] *= alpha; o[qb][eb][1] *= alpha; o[qb][eb][2] *= alpha; o[qb][eb][3] *= alpha;
;           }
;         }
;       }
;       bf16x8 pf[2];
; #pragma unroll
;       for (int qb = 0; qb < 2; ++qb)
;         pf[qb] = mk8(pack2(s[qb][0][0], s[qb][0][1]), pack2(s[qb][0][2], s[qb][0][3]),
.LBB0_527:
	v_mul_f32_e32 v70, 0x3e38aa3b, v52
	v_mul_f32_e32 v66, 0x3e38aa3b, v53
	v_max3_f32 v0, v3, v70, v66
	v_mul_f32_e32 v68, 0x3e38aa3b, v54
	v_mul_f32_e32 v55, 0x3e38aa3b, v55
	v_max3_f32 v0, v0, v68, v55
	v_mul_f32_e32 v56, 0x3e38aa3b, v56
	v_mul_f32_e32 v53, 0x3e38aa3b, v57
	v_max3_f32 v0, v0, v56, v53
	v_mul_f32_e32 v54, 0x3e38aa3b, v58
	v_mul_f32_e32 v52, 0x3e38aa3b, v59
	v_max3_f32 v0, v0, v54, v52
	v_mov_b32_e32 v57, v0
	s_waitcnt lgkmcnt(0)
	s_nop 1
	v_permlane16_swap_b32_e32 v0, v57
	v_max_f32_e32 v0, v0, v57
	v_mov_b32_e32 v57, v0
	s_waitcnt lgkmcnt(0)
	v_mov_b32_e32 v87, v0
	s_nop 1
	v_permlane32_swap_b32_e32 v87, v57
	v_max_f32_e32 v87, v87, v57
	v_sub_f32_e32 v0, v3, v87
	v_exp_f32_e32 v0, v0
	s_nop 0
	v_cmp_neq_f32_e32 vcc, 1.0, v0
	s_cbranch_vccz .LBB0_529
	v_mul_f32_e32 v34, v34, v0
	v_mul_f32_e32 v35, v35, v0
	v_mul_f32_e32 v32, v32, v0
	v_mul_f32_e32 v33, v33, v0
	v_mul_f32_e32 v22, v22, v0
	v_mul_f32_e32 v23, v23, v0
	v_mul_f32_e32 v20, v20, v0
	v_mul_f32_e32 v21, v21, v0
	v_mul_f32_e32 v30, v30, v0
	v_mul_f32_e32 v31, v31, v0
	v_mul_f32_e32 v28, v28, v0
	v_mul_f32_e32 v29, v29, v0
	v_mul_f32_e32 v50, v50, v0
	v_mul_f32_e32 v51, v51, v0
	v_mul_f32_e32 v48, v48, v0
	v_mul_f32_e32 v49, v49, v0
.LBB0_529:
	v_sub_f32_e32 v3, v70, v87
	v_exp_f32_e32 v75, v3
	v_sub_f32_e32 v3, v66, v87
	v_exp_f32_e32 v77, v3
	v_sub_f32_e32 v3, v68, v87
	v_exp_f32_e32 v66, v3
	v_sub_f32_e32 v3, v55, v87
	v_exp_f32_e32 v68, v3
	v_sub_f32_e32 v3, v56, v87
	v_exp_f32_e32 v70, v3
	v_sub_f32_e32 v3, v53, v87
	v_exp_f32_e32 v72, v3
	v_sub_f32_e32 v3, v54, v87
	v_exp_f32_e32 v74, v3
	v_sub_f32_e32 v3, v52, v87
	v_exp_f32_e32 v76, v3
	v_sub_f32_e32 v3, v61, v85
	v_exp_f32_e32 v81, v3
	v_sub_f32_e32 v3, v60, v85
	v_exp_f32_e32 v83, v3
	v_sub_f32_e32 v3, v63, v85
	v_exp_f32_e32 v78, v3
	v_sub_f32_e32 v3, v62, v85
	v_exp_f32_e32 v80, v3
	v_sub_f32_e32 v3, v82, v85
	v_exp_f32_e32 v82, v3
	v_sub_f32_e32 v3, v84, v85
	v_exp_f32_e32 v84, v3
	v_sub_f32_e32 v3, v86, v85
	v_exp_f32_e32 v86, v3
	v_sub_f32_e32 v3, v88, v85
	v_exp_f32_e32 v88, v3
	v_add_u32_e32 v3, v94, v71
	v_add_u32_e32 v69, v94, v69
	ds_read2st64_b64 v[54:57], v3 offset0:48 offset1:52
	ds_read2st64_b64 v[60:63], v69 offset0:48 offset1:52
	v_cvt_pk_bf16_f32 v98, v81, v83
	v_cvt_pk_bf16_f32 v99, v78, v80
	v_cvt_pk_bf16_f32 v100, v82, v84
	s_waitcnt lgkmcnt(0)
	v_mov_b32_e32 v52, v54
	v_mov_b32_e32 v53, v55
	v_mov_b32_e32 v54, v60
	v_mov_b32_e32 v55, v61
	v_cvt_pk_bf16_f32 v101, v86, v88
	v_cvt_pk_bf16_f32 v102, v75, v77
	v_cvt_pk_bf16_f32 v103, v66, v68
	v_cvt_pk_bf16_f32 v104, v70, v72
	v_cvt_pk_bf16_f32 v105, v74, v76
	v_mfma_f32_16x16x32_bf16 v[44:47], v[52:55], v[98:101], v[44:47]
	v_mov_b32_e32 v60, v56
	v_mov_b32_e32 v61, v57
	v_mfma_f32_16x16x32_bf16 v[52:55], v[52:55], v[102:105], v[32:35]
	s_nop 2
	ds_read2st64_b64 v[32:35], v3 offset0:56 offset1:60
	ds_read2st64_b64 v[106:109], v69 offset0:56 offset1:60
	v_mfma_f32_16x16x32_bf16 v[56:59], v[60:63], v[98:101], v[24:27]
	s_waitcnt lgkmcnt(0)
	s_nop 1
	v_mov_b32_e32 v24, v32
	v_mov_b32_e32 v25, v33
	v_mov_b32_e32 v26, v106
	v_mov_b32_e32 v27, v107
	v_mov_b32_e32 v106, v34
	v_mov_b32_e32 v107, v35
	v_mfma_f32_16x16x32_bf16 v[60:63], v[60:63], v[102:105], v[20:23]
	v_mfma_f32_16x16x32_bf16 v[20:23], v[24:27], v[98:101], v[36:39]
	v_mfma_f32_16x16x32_bf16 v[24:27], v[24:27], v[102:105], v[28:31]
	v_mfma_f32_16x16x32_bf16 v[28:31], v[106:109], v[98:101], v[40:43]
	s_nop 0
	ds_read_b128 v[36:39], v73 offset:12288
	s_nop 0
	ds_read_b128 v[40:43], v2 offset:12288
	v_mfma_f32_16x16x32_bf16 v[32:35], v[106:109], v[102:105], v[48:51]
	s_waitcnt lgkmcnt(0)
	v_mfma_f32_16x16x32_bf16 v[48:51], v[36:39], v[8:11], 0
	v_mfma_f32_16x16x32_bf16 v[36:39], v[36:39], v[12:15], 0
	v_mfma_f32_16x16x32_bf16 v[48:51], v[40:43], v[4:7], v[48:51]
	v_mfma_f32_16x16x32_bf16 v[36:39], v[40:43], v[16:19], v[36:39]
	ds_read_b128 v[40:43], v73 offset:14336
	ds_read_b128 v[98:101], v2 offset:14336
	s_waitcnt lgkmcnt(0)
	v_mfma_f32_16x16x32_bf16 v[8:11], v[40:43], v[8:11], 0
	v_mfma_f32_16x16x32_bf16 v[102:105], v[98:101], v[4:7], v[8:11]
	v_mfma_f32_16x16x32_bf16 v[2:5], v[40:43], v[12:15], 0
	s_nop 0
	v_mul_f32_e32 v14, 0x3e38aa3b, v48
	v_mul_f32_e32 v12, 0x3e38aa3b, v49
	v_max3_f32 v6, v85, v14, v12
	v_mul_f32_e32 v13, 0x3e38aa3b, v50
	s_nop 0
	v_mul_f32_e32 v10, 0x3e38aa3b, v51
	v_max3_f32 v6, v6, v13, v10
	v_mul_f32_e32 v11, 0x3e38aa3b, v102
	v_mul_f32_e32 v8, 0x3e38aa3b, v103
	v_max3_f32 v6, v6, v11, v8
	v_mul_f32_e32 v9, 0x3e38aa3b, v104
	v_mul_f32_e32 v7, 0x3e38aa3b, v105
	v_max3_f32 v6, v6, v9, v7
	v_mov_b32_e32 v15, v6
	v_mfma_f32_16x16x32_bf16 v[2:5], v[98:101], v[16:19], v[2:5]
	s_waitcnt lgkmcnt(0)
	s_nop 1
	v_permlane16_swap_b32_e32 v6, v15
	v_max_f32_e32 v6, v6, v15
	v_mov_b32_e32 v15, v6
	s_waitcnt lgkmcnt(0)
	s_nop 1
	v_permlane32_swap_b32_e32 v6, v15
	v_max_f32_e32 v15, v6, v15
	v_sub_f32_e32 v6, v85, v15
	v_exp_f32_e32 v6, v6
	s_nop 0
	v_cmp_neq_f32_e32 vcc, 1.0, v6
	s_cbranch_vccz .LBB0_531
	v_mul_f32_e32 v46, v46, v6
	v_mul_f32_e32 v47, v47, v6
	v_mul_f32_e32 v44, v44, v6
	v_mul_f32_e32 v45, v45, v6
	v_mul_f32_e32 v58, v58, v6
	v_mul_f32_e32 v59, v59, v6
	v_mul_f32_e32 v56, v56, v6
	v_mul_f32_e32 v57, v57, v6
	v_mul_f32_e32 v22, v22, v6
	v_mul_f32_e32 v23, v23, v6
	v_mul_f32_e32 v20, v20, v6
	v_mul_f32_e32 v21, v21, v6
	v_mul_f32_e32 v30, v30, v6
	v_mul_f32_e32 v31, v31, v6
	v_mul_f32_e32 v28, v28, v6
	v_mul_f32_e32 v29, v29, v6
.LBB0_531:
	v_mul_f32_e32 v40, 0x3e38aa3b, v36
	v_mul_f32_e32 v19, 0x3e38aa3b, v37
	v_max3_f32 v16, v87, v40, v19
	v_mul_f32_e32 v36, 0x3e38aa3b, v38
	v_mul_f32_e32 v17, 0x3e38aa3b, v39
	v_max3_f32 v37, v16, v36, v17
	v_mul_f32_e32 v18, 0x3e38aa3b, v2
	v_mul_f32_e32 v16, 0x3e38aa3b, v3
	v_max3_f32 v2, v37, v18, v16
	v_mul_f32_e32 v4, 0x3e38aa3b, v4
	v_mul_f32_e32 v3, 0x3e38aa3b, v5
	v_max3_f32 v2, v2, v4, v3
	v_mov_b32_e32 v5, v2
	s_waitcnt lgkmcnt(0)
	s_nop 1
	v_permlane16_swap_b32_e32 v2, v5
	v_max_f32_e32 v2, v2, v5
	v_mov_b32_e32 v5, v2
	s_waitcnt lgkmcnt(0)
	s_nop 1
	v_permlane32_swap_b32_e32 v2, v5
	v_max_f32_e32 v5, v2, v5
	v_sub_f32_e32 v2, v87, v5
	v_exp_f32_e32 v2, v2
	s_nop 0
	v_cmp_neq_f32_e32 vcc, 1.0, v2
	s_cbranch_vccz .LBB0_514
	v_mul_f32_e32 v54, v54, v2
	v_mul_f32_e32 v55, v55, v2
	v_mul_f32_e32 v52, v52, v2
	v_mul_f32_e32 v53, v53, v2
	v_mul_f32_e32 v62, v62, v2
	v_mul_f32_e32 v63, v63, v2
	v_mul_f32_e32 v60, v60, v2
	v_mul_f32_e32 v61, v61, v2
	v_mul_f32_e32 v26, v26, v2
	v_mul_f32_e32 v27, v27, v2
	v_mul_f32_e32 v24, v24, v2
	v_mul_f32_e32 v25, v25, v2
	v_mul_f32_e32 v34, v34, v2
	v_mul_f32_e32 v35, v35, v2
	v_mul_f32_e32 v32, v32, v2
	v_mul_f32_e32 v33, v33, v2
	s_branch .LBB0_514

; __device__ __forceinline__ float fexp2(float x) { return __builtin_amdgcn_exp2f(x); }
; template <int DKA, int DKB, int DV, bool BAND, bool SINK> ...
;     ...
;       for (int kb2 = 0; kb2 < 2; ++kb2) {
;         const int kb = kk * 2 + kb2;
;         bf16x8 kf[KS];
; #pragma unroll
;         for (int ks = 0; ks < KS; ++ks) {
;           if (ks < KSA) {
;             if (DKA == 128) kf[ks] = *(const bf16x8*)(kst + (kb * 16 + fr) * 256 + (((ks * 4 + fq) ^ fr) * 16));
;             else kf[ks] = *(const bf16x8*)(kst + (kb * 16 + fr) * 128 + (((ks * 4 + fq) ^ swz8) * 16));
;           } else {
;             kf[ks] = *(const bf16x8*)(kst + KASZ + (kb * 16 + fr) * 128 + ((((ks - KSA) * 4 + fq) ^ swz8) * 16));
;           }
;         }
; #pragma unroll
;         for (int qb = 0; qb < 2; ++qb) {
;           f32x4 a = (f32x4){0.f, 0.f, 0.f, 0.f};
; #pragma unroll
;           for (int ks = 0; ks < KS; ++ks) a = mfma16(kf[ks], qf[qb][ks], a);
;           s[qb][kb2] = a;
;         }
;       }
; #pragma unroll
;       for (int qb = 0; qb < 2; ++qb) {
;         float mx = mrun[qb];
;         const int qp = qpos0 + wave * 32 + qb * 16 + fr;
; #pragma unroll
;         for (int kb2 = 0; kb2 < 2; ++kb2)
; #pragma unroll
;           for (int j = 0; j < 4; ++j) {
;             float v = s[qb][kb2][j] * scale2;
;             if (BAND && k0 < 2048) {
;               int d = qp - (k0 + (kk * 2 + kb2) * 16 + fq * 4 + j);
;               if (d > 128 || d < -128) v = -1e30f;
;             }
;             s[qb][kb2][j] = v;
;             mx = fmaxf(mx, v);
;           }
;         mx = fmaxf(mx, __shfl_xor(mx, 16));
;         mx = fmaxf(mx, __shfl_xor(mx, 32));
;         const float alpha = fexp2(mrun[qb] - mx);
;         mrun[qb] = mx;
;         float ls = 0.f;
; #pragma unroll
;         for (int kb2 = 0; kb2 < 2; ++kb2)
; #pragma unroll
;           for (int j = 0; j < 4; ++j) {
;             float pv = fexp2(s[qb][kb2][j] - mx);
;             s[qb][kb2][j] = pv;
;             ls += pv;
;           }
;         lrun[qb] = lrun[qb] * alpha + ls;
;         if (__any(alpha != 1.f)) {
; #pragma unroll
;           for (int eb = 0; eb < EB; ++eb) {
;             o[qb][eb][0] *= alpha; o[qb][eb][1] *= alpha; o[qb][eb][2] *= alpha; o[qb][eb][3] *= alpha;
;           }
;         }
.LBB0_559:
	s_add_i32 s8, s1, 4
	s_cmp_lt_i32 s8, s46
	s_cselect_b32 s8, 0, s46
	s_cselect_b32 s9, s65, 0x800
	s_add_i32 s11, s87, 0xffffe000
	s_and_b32 s57, s11, 0x2000
	v_cmp_lt_i32_e32 vcc, v200, v198
	v_or_b32_e32 v54, s57, v71
	v_add_u32_e32 v85, v54, v73
	v_cndmask_b32_e32 v50, v197, v200, vcc
	v_cmp_lt_i32_e32 vcc, v199, v198
	v_lshlrev_b32_e32 v82, 2, v50
	v_add_u32_e32 v68, v54, v74
	v_cndmask_b32_e32 v50, v197, v199, vcc
	v_lshlrev_b32_e32 v83, 2, v50
	ds_read_b128 v[50:53], v85
	ds_read_b128 v[54:57], v68
	s_waitcnt lgkmcnt(0)
	v_mfma_f32_16x16x32_bf16 v[86:89], v[50:53], v[2:5], 0
	s_lshl_b32 s8, s8, 6
	s_sub_i32 s10, s9, s8
	s_add_i32 s10, s34, s10
	v_mfma_f32_16x16x32_bf16 v[50:53], v[50:53], v[10:13], 0
	s_sub_i32 s10, s10, 64
	s_cmpk_lt_i32 s10, 0x800
	s_cselect_b64 s[66:67], -1, 0
	v_mfma_f32_16x16x32_bf16 v[86:89], v[54:57], v[6:9], v[86:89]
	s_sub_i32 s8, s8, s9
	v_mfma_f32_16x16x32_bf16 v[50:53], v[54:57], v[14:17], v[50:53]
	ds_read_b128 v[54:57], v85 offset:2048
	ds_read_b128 v[90:93], v68 offset:2048
	s_nop 3
	v_mul_f32_e32 v64, 0x3e38aa3b, v86
	s_waitcnt lgkmcnt(0)
	v_mfma_f32_16x16x32_bf16 v[94:97], v[54:57], v[2:5], 0
	v_mfma_f32_16x16x32_bf16 v[102:105], v[90:93], v[6:9], v[94:97]
	s_nop 6
	v_add_u32_e32 v94, s8, v79
	v_add_u32_e32 v66, 51, v94
	v_cmp_gt_u32_e32 vcc, s56, v66
	v_add_u32_e32 v66, 50, v94
	s_and_b64 s[16:17], s[66:67], vcc
	v_cmp_gt_u32_e32 vcc, s56, v66
	v_add_u32_e32 v84, 49, v94
	s_and_b64 s[18:19], s[66:67], vcc
	v_cmp_gt_u32_e32 vcc, s56, v84
	v_add_u32_e32 v84, 48, v94
	v_mul_f32_e32 v66, 0x3e38aa3b, v88
	s_and_b64 s[20:21], s[66:67], vcc
	v_cmp_gt_u32_e32 vcc, s56, v84
	v_add_u32_e32 v84, 35, v94
	v_cndmask_b32_e64 v99, v66, v207, s[20:21]
	v_mul_f32_e32 v66, 0x3e38aa3b, v89
	s_and_b64 s[22:23], s[66:67], vcc
	v_cmp_gt_u32_e32 vcc, s56, v84
	v_add_u32_e32 v84, 34, v94
	v_cndmask_b32_e64 v97, v64, v207, s[16:17]
	v_mul_f32_e32 v64, 0x3e38aa3b, v87
	v_cndmask_b32_e64 v100, v66, v207, s[22:23]
	v_mul_f32_e32 v66, 0x3e38aa3b, v102
	s_and_b64 s[8:9], s[66:67], vcc
	v_cmp_gt_u32_e32 vcc, s56, v84
	v_add_u32_e32 v84, 33, v94
	v_cndmask_b32_e64 v98, v64, v207, s[18:19]
	v_cndmask_b32_e64 v101, v66, v207, s[8:9]
	v_mul_f32_e32 v66, 0x3e38aa3b, v103
	s_and_b64 s[10:11], s[66:67], vcc
	v_cmp_gt_u32_e32 vcc, s56, v84
	v_add_u32_e32 v84, 32, v94
	v_max3_f32 v64, v80, v97, v98
	v_cndmask_b32_e64 v102, v66, v207, s[10:11]
	v_mul_f32_e32 v66, 0x3e38aa3b, v104
	s_and_b64 s[12:13], s[66:67], vcc
	v_cmp_gt_u32_e32 vcc, s56, v84
	v_max3_f32 v64, v64, v99, v100
	v_cndmask_b32_e64 v103, v66, v207, s[12:13]
	v_mul_f32_e32 v66, 0x3e38aa3b, v105
	s_and_b64 s[14:15], s[66:67], vcc
	v_max3_f32 v64, v64, v101, v102
	v_cndmask_b32_e64 v104, v66, v207, s[14:15]
	v_max3_f32 v64, v64, v103, v104
	v_mov_b32_e32 v66, v64
	v_mfma_f32_16x16x32_bf16 v[54:57], v[54:57], v[10:13], 0
	s_waitcnt lgkmcnt(0)
	s_nop 1
	v_permlane16_swap_b32_e32 v64, v66
	v_max_f32_e32 v64, v64, v66
	v_mov_b32_e32 v66, v64
	v_mfma_f32_16x16x32_bf16 v[54:57], v[90:93], v[14:17], v[54:57]
	s_waitcnt lgkmcnt(0)
	v_mov_b32_e32 v95, v64
	s_nop 1
	v_permlane32_swap_b32_e32 v95, v66
	v_max_f32_e32 v95, v95, v66
	v_sub_f32_e32 v64, v80, v95
	v_exp_f32_e32 v64, v64
	s_nop 0
	v_cmp_neq_f32_e32 vcc, 1.0, v64
	s_cbranch_vccz .LBB0_561
	v_mul_f32_e32 v44, v44, v64
	v_mul_f32_e32 v45, v45, v64
	v_mul_f32_e32 v42, v42, v64
	v_mul_f32_e32 v43, v43, v64
	v_mul_f32_e32 v36, v36, v64
	v_mul_f32_e32 v37, v37, v64
	v_mul_f32_e32 v34, v34, v64
	v_mul_f32_e32 v35, v35, v64
	v_mul_f32_e32 v40, v40, v64
	v_mul_f32_e32 v41, v41, v64
	v_mul_f32_e32 v38, v38, v64
	v_mul_f32_e32 v39, v39, v64
	v_mul_f32_e32 v48, v48, v64
	v_mul_f32_e32 v49, v49, v64
	v_mul_f32_e32 v46, v46, v64
	v_mul_f32_e32 v47, v47, v64
.LBB0_561:
	v_add_u32_e32 v66, 0x43, v94
	v_cmp_gt_u32_e32 vcc, s56, v66
	v_mul_f32_e32 v50, 0x3e38aa3b, v50
	s_and_b64 vcc, s[66:67], vcc
	v_add_u32_e32 v66, 0x42, v94
	v_cndmask_b32_e32 v50, v50, v207, vcc
	v_cmp_gt_u32_e32 vcc, s56, v66
	v_mul_f32_e32 v51, 0x3e38aa3b, v51
	s_and_b64 vcc, s[66:67], vcc
	v_add_u32_e32 v80, 0x41, v94
	v_cndmask_b32_e32 v51, v51, v207, vcc
	v_cmp_gt_u32_e32 vcc, s56, v80
	v_mul_f32_e32 v52, 0x3e38aa3b, v52
	s_and_b64 vcc, s[66:67], vcc
	v_add_u32_e32 v80, 64, v94
	v_cndmask_b32_e32 v52, v52, v207, vcc
	v_cmp_gt_u32_e32 vcc, s56, v80
	v_mul_f32_e32 v53, 0x3e38aa3b, v53
	s_and_b64 vcc, s[66:67], vcc
	v_max3_f32 v66, v81, v50, v51
	v_cndmask_b32_e32 v53, v53, v207, vcc
	v_mul_f32_e32 v54, 0x3e38aa3b, v54
	v_mul_f32_e32 v55, 0x3e38aa3b, v55
	v_max3_f32 v66, v66, v52, v53
	v_cndmask_b32_e64 v54, v54, v207, s[16:17]
	v_cndmask_b32_e64 v55, v55, v207, s[18:19]
	v_mul_f32_e32 v56, 0x3e38aa3b, v56
	v_mul_f32_e32 v57, 0x3e38aa3b, v57
	v_max3_f32 v66, v66, v54, v55
	v_cndmask_b32_e64 v56, v56, v207, s[20:21]
	v_cndmask_b32_e64 v57, v57, v207, s[22:23]
	v_max3_f32 v66, v66, v56, v57
	v_mov_b32_e32 v80, v66
	s_waitcnt lgkmcnt(0)
	s_nop 1
	v_permlane16_swap_b32_e32 v66, v80
	v_max_f32_e32 v66, v66, v80
	v_mov_b32_e32 v80, v66
	s_waitcnt lgkmcnt(0)
	v_mov_b32_e32 v96, v66
	s_nop 1
	v_permlane32_swap_b32_e32 v96, v80
	v_max_f32_e32 v96, v96, v80
	v_sub_f32_e32 v66, v81, v96
	v_exp_f32_e32 v66, v66
	s_nop 0
	v_cmp_neq_f32_e32 vcc, 1.0, v66
	s_cbranch_vccz .LBB0_563
	v_mul_f32_e32 v24, v24, v66
	v_mul_f32_e32 v25, v25, v66
	v_mul_f32_e32 v22, v22, v66
	v_mul_f32_e32 v23, v23, v66
	v_mul_f32_e32 v20, v20, v66
	v_mul_f32_e32 v21, v21, v66
	v_mul_f32_e32 v18, v18, v66
	v_mul_f32_e32 v19, v19, v66
	v_mul_f32_e32 v28, v28, v66
	v_mul_f32_e32 v29, v29, v66
	v_mul_f32_e32 v26, v26, v66
	v_mul_f32_e32 v27, v27, v66
	v_mul_f32_e32 v32, v32, v66
	v_mul_f32_e32 v33, v33, v66
	v_mul_f32_e32 v30, v30, v66
	v_mul_f32_e32 v31, v31, v66
; template <int DKA, int DKB, int DV, bool BAND, bool SINK> ...
;     ...
; #pragma unroll
;         for (int qb = 0; qb < 2; ++qb) {
;           f32x4 a = (f32x4){0.f, 0.f, 0.f, 0.f};
; #pragma unroll
;           for (int ks = 0; ks < KS; ++ks) a = mfma16(kf[ks], qf[qb][ks], a);
;           s[qb][kb2] = a;
;         }
;       }
; #pragma unroll
;       for (int qb = 0; qb < 2; ++qb) {
;         float mx = mrun[qb];
;         const int qp = qpos0 + wave * 32 + qb * 16 + fr;
; #pragma unroll
;         for (int kb2 = 0; kb2 < 2; ++kb2)
; #pragma unroll
;           for (int j = 0; j < 4; ++j) {
;             float v = s[qb][kb2][j] * scale2;
;             if (BAND && k0 < 2048) {
;               int d = qp - (k0 + (kk * 2 + kb2) * 16 + fq * 4 + j);
;               if (d > 128 || d < -128) v = -1e30f;
;             }
;             s[qb][kb2][j] = v;
;             mx = fmaxf(mx, v);
;           }
;         mx = fmaxf(mx, __shfl_xor(mx, 16));
;         mx = fmaxf(mx, __shfl_xor(mx, 32));
;         const float alpha = fexp2(mrun[qb] - mx);
;         mrun[qb] = mx;
;         float ls = 0.f;
; #pragma unroll
;         for (int kb2 = 0; kb2 < 2; ++kb2)
; #pragma unroll
;           for (int j = 0; j < 4; ++j) {
;             float pv = fexp2(s[qb][kb2][j] - mx);
;             s[qb][kb2][j] = pv;
;             ls += pv;
;           }
;         lrun[qb] = lrun[qb] * alpha + ls;
;         if (__any(alpha != 1.f)) {
; #pragma unroll
;           for (int eb = 0; eb < EB; ++eb) {
;             o[qb][eb][0] *= alpha; o[qb][eb][1] *= alpha; o[qb][eb][2] *= alpha; o[qb][eb][3] *= alpha;
;           }
;         }
;       }
;       bf16x8 pf[2];
; #pragma unroll
;       for (int qb = 0; qb < 2; ++qb)
;         pf[qb] = mk8(pack2(s[qb][0][0], s[qb][0][1]), pack2(s[qb][0][2], s[qb][0][3]),
;                      pack2(s[qb][1][0], s[qb][1][1]), pack2(s[qb][1][2], s[qb][1][3]));
; #pragma unroll
;       for (int eb = 0; eb < EB; ++eb) {
;         const char* vrow = vbuf + (eb * 16 + fr) * 128 + (fq & 1) * 8;
;         uint2 v0 = *(const uint2*)(vrow + (((kk * 4 + (fq >> 1)) ^ swz8) * 16));
;         uint2 v1 = *(const uint2*)(vrow + (((kk * 4 + 2 + (fq >> 1)) ^ swz8) * 16));
;         bf16x8 vf = mk8(v0.x, v0.y, v1.x, v1.y);
; #pragma unroll
;         for (int qb = 0; qb < 2; ++qb) o[qb][eb] = mfma16(vf, pf[qb], o[qb][eb]);
;       }
.LBB0_563:
	v_sub_f32_e32 v50, v50, v96
	v_exp_f32_e32 v86, v50
	v_sub_f32_e32 v50, v51, v96
	v_exp_f32_e32 v87, v50
	v_sub_f32_e32 v50, v52, v96
	v_exp_f32_e32 v88, v50
	v_sub_f32_e32 v50, v53, v96
	v_exp_f32_e32 v89, v50
	v_sub_f32_e32 v50, v54, v96
	v_exp_f32_e32 v90, v50
	v_sub_f32_e32 v50, v55, v96
	v_exp_f32_e32 v91, v50
	v_sub_f32_e32 v50, v56, v96
	v_exp_f32_e32 v92, v50
	v_sub_f32_e32 v50, v57, v96
	v_exp_f32_e32 v93, v50
	v_sub_f32_e32 v50, v97, v95
	v_add_u32_e32 v84, s57, v72
	v_exp_f32_e32 v97, v50
	v_sub_f32_e32 v50, v98, v95
	v_exp_f32_e32 v98, v50
	v_sub_f32_e32 v50, v99, v95
	v_add_u32_e32 v80, v84, v75
	v_add_u32_e32 v81, v84, v76
	v_exp_f32_e32 v99, v50
	v_sub_f32_e32 v50, v100, v95
	ds_read2st64_b64 v[106:109], v80 offset0:32 offset1:36
	ds_read2st64_b64 v[110:113], v81 offset0:32 offset1:36
	v_exp_f32_e32 v100, v50
	v_sub_f32_e32 v50, v101, v95
	v_exp_f32_e32 v101, v50
	v_sub_f32_e32 v50, v102, v95
	v_exp_f32_e32 v102, v50
	v_sub_f32_e32 v50, v103, v95
	v_exp_f32_e32 v103, v50
	v_sub_f32_e32 v50, v104, v95
	v_exp_f32_e32 v104, v50
	s_waitcnt lgkmcnt(0)
	v_mov_b32_e32 v116, v110
	v_mov_b32_e32 v117, v111
	v_mov_b32_e32 v110, v108
	v_mov_b32_e32 v111, v109
	v_cvt_pk_bf16_f32 v50, v97, v98
	v_cvt_pk_bf16_f32 v51, v99, v100
	v_cvt_pk_bf16_f32 v52, v101, v102
	v_cvt_pk_bf16_f32 v53, v103, v104
	v_cvt_pk_bf16_f32 v54, v86, v87
	v_cvt_pk_bf16_f32 v55, v88, v89
	v_cvt_pk_bf16_f32 v56, v90, v91
	v_cvt_pk_bf16_f32 v57, v92, v93
	v_mov_b32_e32 v114, v106
	v_mov_b32_e32 v115, v107
	v_mfma_f32_16x16x32_bf16 v[34:37], v[110:113], v[50:53], v[34:37]
	v_mfma_f32_16x16x32_bf16 v[18:21], v[110:113], v[54:57], v[18:21]
	ds_read2st64_b64 v[106:109], v80 offset0:40 offset1:44
	ds_read2st64_b64 v[110:113], v81 offset0:40 offset1:44
	v_add_u32_e32 v80, 19, v94
	v_cmp_gt_u32_e32 vcc, s56, v80
	v_mfma_f32_16x16x32_bf16 v[42:45], v[114:117], v[50:53], v[42:45]
	v_add_u32_e32 v80, 18, v94
	s_and_b64 s[16:17], s[66:67], vcc
	v_cmp_gt_u32_e32 vcc, s56, v80
	v_mfma_f32_16x16x32_bf16 v[22:25], v[114:117], v[54:57], v[22:25]
	s_waitcnt lgkmcnt(0)
	v_mov_b32_e32 v114, v106
	v_mov_b32_e32 v115, v107
	v_mov_b32_e32 v116, v110
	v_mov_b32_e32 v117, v111
	v_mov_b32_e32 v110, v108
	v_mov_b32_e32 v111, v109
	v_mfma_f32_16x16x32_bf16 v[38:41], v[114:117], v[50:53], v[38:41]
	v_add_u32_e32 v81, 17, v94
	s_and_b64 s[18:19], s[66:67], vcc
	v_cmp_gt_u32_e32 vcc, s56, v81
	v_mfma_f32_16x16x32_bf16 v[26:29], v[114:117], v[54:57], v[26:29]
	v_add_u32_e32 v81, 16, v94
	s_and_b64 s[20:21], s[66:67], vcc
	v_cmp_gt_u32_e32 vcc, s56, v81
	v_mfma_f32_16x16x32_bf16 v[46:49], v[110:113], v[50:53], v[46:49]
	v_add_u32_e32 v81, 3, v94
	s_and_b64 s[22:23], s[66:67], vcc
	v_cmp_gt_u32_e32 vcc, s56, v81
	v_mfma_f32_16x16x32_bf16 v[30:33], v[110:113], v[54:57], v[30:33]
	ds_read_b128 v[50:53], v85 offset:4096
	ds_read_b128 v[54:57], v68 offset:4096
	s_and_b64 vcc, s[66:67], vcc
	v_add_u32_e32 v81, 2, v94
	s_waitcnt lgkmcnt(0)
	v_mfma_f32_16x16x32_bf16 v[106:109], v[50:53], v[2:5], 0
	v_mfma_f32_16x16x32_bf16 v[50:53], v[50:53], v[10:13], 0
	v_mfma_f32_16x16x32_bf16 v[112:115], v[54:57], v[6:9], v[106:109]
	v_mfma_f32_16x16x32_bf16 v[50:53], v[54:57], v[14:17], v[50:53]
	ds_read_b128 v[54:57], v85 offset:6144
	s_nop 3
	ds_read_b128 v[106:109], v68 offset:6144
	s_nop 0
	v_mul_f32_e32 v80, 0x3e38aa3b, v114
	v_mul_f32_e32 v68, 0x3e38aa3b, v112
	s_waitcnt lgkmcnt(0)
	v_mfma_f32_16x16x32_bf16 v[116:119], v[54:57], v[2:5], 0
	v_cndmask_b32_e64 v111, v68, v207, s[16:17]
	v_mul_f32_e32 v68, 0x3e38aa3b, v113
	v_cndmask_b32_e64 v110, v68, v207, s[18:19]
	v_mfma_f32_16x16x32_bf16 v[54:57], v[54:57], v[10:13], 0
	v_max3_f32 v68, v95, v111, v110
	v_mfma_f32_16x16x32_bf16 v[116:119], v[106:109], v[6:9], v[116:119]
	v_mfma_f32_16x16x32_bf16 v[54:57], v[106:109], v[14:17], v[54:57]
	v_cndmask_b32_e64 v109, v80, v207, s[20:21]
	v_mul_f32_e32 v80, 0x3e38aa3b, v115
	v_cndmask_b32_e64 v108, v80, v207, s[22:23]
	s_nop 3
	v_mul_f32_e32 v80, 0x3e38aa3b, v116
	v_cndmask_b32_e32 v107, v80, v207, vcc
	v_cmp_gt_u32_e32 vcc, s56, v81
	v_mul_f32_e32 v80, 0x3e38aa3b, v117
	s_and_b64 vcc, s[66:67], vcc
	v_add_u32_e32 v81, 1, v94
	v_cndmask_b32_e32 v106, v80, v207, vcc
	v_cmp_gt_u32_e32 vcc, s56, v81
	v_mul_f32_e32 v80, 0x3e38aa3b, v118
	s_and_b64 vcc, s[66:67], vcc
	v_cndmask_b32_e32 v105, v80, v207, vcc
	v_cmp_gt_u32_e32 vcc, s56, v94
	v_max3_f32 v68, v68, v109, v108
	v_mul_f32_e32 v80, 0x3e38aa3b, v119
	s_and_b64 vcc, s[66:67], vcc
	v_max3_f32 v68, v68, v107, v106
	v_cndmask_b32_e32 v85, v80, v207, vcc
	v_max3_f32 v68, v68, v105, v85
	v_mov_b32_e32 v80, v68
	s_waitcnt lgkmcnt(0)
	s_nop 1
	v_permlane16_swap_b32_e32 v68, v80
	v_max_f32_e32 v68, v68, v80
	v_mov_b32_e32 v80, v68
	s_waitcnt lgkmcnt(0)
	s_nop 1
	v_permlane32_swap_b32_e32 v68, v80
	v_max_f32_e32 v80, v68, v80
	v_sub_f32_e32 v68, v95, v80
	v_exp_f32_e32 v68, v68
	s_nop 0
	v_cmp_neq_f32_e32 vcc, 1.0, v68
	s_cbranch_vccz .LBB0_565
	v_mul_f32_e32 v44, v44, v68
	v_mul_f32_e32 v45, v45, v68
	v_mul_f32_e32 v42, v42, v68
	v_mul_f32_e32 v43, v43, v68
	v_mul_f32_e32 v36, v36, v68
	v_mul_f32_e32 v37, v37, v68
	v_mul_f32_e32 v34, v34, v68
	v_mul_f32_e32 v35, v35, v68
	v_mul_f32_e32 v40, v40, v68
	v_mul_f32_e32 v41, v41, v68
	v_mul_f32_e32 v38, v38, v68
	v_mul_f32_e32 v39, v39, v68
	v_mul_f32_e32 v48, v48, v68
	v_mul_f32_e32 v49, v49, v68
	v_mul_f32_e32 v46, v46, v68
	v_mul_f32_e32 v47, v47, v68
.LBB0_565:
	v_mul_f32_e32 v50, 0x3e38aa3b, v50
	v_cndmask_b32_e64 v113, v50, v207, s[8:9]
	v_mul_f32_e32 v50, 0x3e38aa3b, v51
	v_mul_f32_e32 v51, 0x3e38aa3b, v52
	v_cndmask_b32_e64 v95, v51, v207, s[12:13]
	v_mul_f32_e32 v51, 0x3e38aa3b, v53
	v_cndmask_b32_e64 v94, v51, v207, s[14:15]
	v_mul_f32_e32 v51, 0x3e38aa3b, v54
	v_cndmask_b32_e64 v112, v50, v207, s[10:11]
	v_cndmask_b32_e64 v54, v51, v207, s[16:17]
	v_mul_f32_e32 v51, 0x3e38aa3b, v55
	v_max3_f32 v50, v96, v113, v112
	v_cndmask_b32_e64 v53, v51, v207, s[18:19]
	v_mul_f32_e32 v51, 0x3e38aa3b, v56
	v_max3_f32 v50, v50, v95, v94
	v_cndmask_b32_e64 v52, v51, v207, s[20:21]
	v_mul_f32_e32 v51, 0x3e38aa3b, v57
	v_max3_f32 v50, v50, v54, v53
	v_cndmask_b32_e64 v51, v51, v207, s[22:23]
	v_max3_f32 v50, v50, v52, v51
	v_mov_b32_e32 v55, v50
	s_waitcnt lgkmcnt(0)
	s_nop 1
	v_permlane16_swap_b32_e32 v50, v55
	v_max_f32_e32 v50, v50, v55
	v_mov_b32_e32 v55, v50
	s_waitcnt lgkmcnt(0)
	v_mov_b32_e32 v81, v50
	s_nop 1
	v_permlane32_swap_b32_e32 v81, v55
	v_max_f32_e32 v81, v81, v55
	v_sub_f32_e32 v50, v96, v81
	v_exp_f32_e32 v50, v50
	s_nop 0
	v_cmp_neq_f32_e32 vcc, 1.0, v50
	s_cbranch_vccz .LBB0_556
	v_mul_f32_e32 v24, v24, v50
	v_mul_f32_e32 v25, v25, v50
	v_mul_f32_e32 v22, v22, v50
	v_mul_f32_e32 v23, v23, v50
	v_mul_f32_e32 v20, v20, v50
	v_mul_f32_e32 v21, v21, v50
	v_mul_f32_e32 v18, v18, v50
	v_mul_f32_e32 v19, v19, v50
	v_mul_f32_e32 v28, v28, v50
	v_mul_f32_e32 v29, v29, v50
	v_mul_f32_e32 v26, v26, v50
	v_mul_f32_e32 v27, v27, v50
	v_mul_f32_e32 v32, v32, v50
	v_mul_f32_e32 v33, v33, v50
	v_mul_f32_e32 v30, v30, v50
	v_mul_f32_e32 v31, v31, v50
	s_branch .LBB0_556

; __device__ __forceinline__ float fexp2(float x) { return __builtin_amdgcn_exp2f(x); }
; template <int DKA, int DKB, int DV, bool BAND, bool SINK> ...
;     ...
;       for (int kb2 = 0; kb2 < 2; ++kb2) {
;         const int kb = kk * 2 + kb2;
;         bf16x8 kf[KS];
; #pragma unroll
;         for (int ks = 0; ks < KS; ++ks) {
;           if (ks < KSA) {
;             if (DKA == 128) kf[ks] = *(const bf16x8*)(kst + (kb * 16 + fr) * 256 + (((ks * 4 + fq) ^ fr) * 16));
;             else kf[ks] = *(const bf16x8*)(kst + (kb * 16 + fr) * 128 + (((ks * 4 + fq) ^ swz8) * 16));
;           } else {
;             kf[ks] = *(const bf16x8*)(kst + KASZ + (kb * 16 + fr) * 128 + ((((ks - KSA) * 4 + fq) ^ swz8) * 16));
;           }
;         }
; #pragma unroll
;         for (int qb = 0; qb < 2; ++qb) {
;           f32x4 a = (f32x4){0.f, 0.f, 0.f, 0.f};
; #pragma unroll
;           for (int ks = 0; ks < KS; ++ks) a = mfma16(kf[ks], qf[qb][ks], a);
;           s[qb][kb2] = a;
;         }
;       }
; #pragma unroll
;       for (int qb = 0; qb < 2; ++qb) {
;         float mx = mrun[qb];
;         const int qp = qpos0 + wave * 32 + qb * 16 + fr;
; #pragma unroll
;         for (int kb2 = 0; kb2 < 2; ++kb2)
; #pragma unroll
;           for (int j = 0; j < 4; ++j) {
;             float v = s[qb][kb2][j] * scale2;
;             if (BAND && k0 < 2048) {
;               int d = qp - (k0 + (kk * 2 + kb2) * 16 + fq * 4 + j);
;               if (d > 128 || d < -128) v = -1e30f;
;             }
;             s[qb][kb2][j] = v;
;             mx = fmaxf(mx, v);
;           }
;         mx = fmaxf(mx, __shfl_xor(mx, 16));
;         mx = fmaxf(mx, __shfl_xor(mx, 32));
;         const float alpha = fexp2(mrun[qb] - mx);
;         mrun[qb] = mx;
;         float ls = 0.f;
; #pragma unroll
;         for (int kb2 = 0; kb2 < 2; ++kb2)
; #pragma unroll
;           for (int j = 0; j < 4; ++j) {
;             float pv = fexp2(s[qb][kb2][j] - mx);
;             s[qb][kb2][j] = pv;
;             ls += pv;
;           }
;         lrun[qb] = lrun[qb] * alpha + ls;
;         if (__any(alpha != 1.f)) {
; #pragma unroll
;           for (int eb = 0; eb < EB; ++eb) {
;             o[qb][eb][0] *= alpha; o[qb][eb][1] *= alpha; o[qb][eb][2] *= alpha; o[qb][eb][3] *= alpha;
;           }
;         }
.LBB0_1542:
	s_and_b32 s0, s45, 1
	s_mul_i32 s1, s0, 0x6000
	v_cmp_lt_i32_e32 vcc, v200, v198
	v_or_b32_e32 v119, s1, v156
	v_add_u32_e32 v174, v119, v158
	v_cndmask_b32_e32 v114, v197, v200, vcc
	v_cmp_lt_i32_e32 vcc, v199, v198
	v_lshlrev_b32_e32 v141, 2, v114
	v_add_u32_e32 v173, v119, v159
	v_cndmask_b32_e32 v114, v197, v199, vcc
	v_lshlrev_b32_e32 v139, 2, v114
	ds_read_b128 v[114:117], v174
	ds_read_b128 v[122:125], v173
	v_add_u32_e32 v172, v119, v160
	v_or_b32_e32 v118, s1, v155
	ds_read_b128 v[176:179], v172
	v_add_u32_e32 v171, v119, v161
	v_add_u32_e32 v145, v118, v162
	v_add_u32_e32 v143, v118, v163
	s_waitcnt lgkmcnt(0)
	v_mfma_f32_16x16x32_bf16 v[118:121], v[114:117], v[2:5], 0
	ds_read_b128 v[180:183], v171
	ds_read_b128 v[184:187], v145 offset:16384
	ds_read_b128 v[188:191], v143 offset:16384
	v_mfma_f32_16x16x32_bf16 v[114:117], v[114:117], v[26:29], 0
	v_mfma_f32_16x16x32_bf16 v[118:121], v[122:125], v[6:9], v[118:121]
	v_mfma_f32_16x16x32_bf16 v[114:117], v[122:125], v[30:33], v[114:117]
	v_mfma_f32_16x16x32_bf16 v[118:121], v[176:179], v[10:13], v[118:121]
	v_mfma_f32_16x16x32_bf16 v[114:117], v[176:179], v[34:37], v[114:117]
	s_waitcnt lgkmcnt(0)
	v_mfma_f32_16x16x32_bf16 v[118:121], v[180:183], v[14:17], v[118:121]
	v_mfma_f32_16x16x32_bf16 v[114:117], v[180:183], v[38:41], v[114:117]
	v_mfma_f32_16x16x32_bf16 v[118:121], v[184:187], v[18:21], v[118:121]
	v_mfma_f32_16x16x32_bf16 v[114:117], v[184:187], v[42:45], v[114:117]
	v_mfma_f32_16x16x32_bf16 v[118:121], v[188:191], v[22:25], v[118:121]
	v_mfma_f32_16x16x32_bf16 v[114:117], v[188:191], v[46:49], v[114:117]
	ds_read_b128 v[122:125], v174 offset:4096
	ds_read_b128 v[176:179], v173 offset:4096
	ds_read_b128 v[180:183], v172 offset:4096
	ds_read_b128 v[184:187], v171 offset:4096
	ds_read_b128 v[188:191], v145 offset:18432
	ds_read_b128 v[192:195], v143 offset:18432
	s_nop 0
	v_mul_f32_e32 v175, 0x3dd53b94, v118
	v_mul_f32_e32 v118, 0x3dd53b94, v119
	s_waitcnt lgkmcnt(0)
	v_mfma_f32_16x16x32_bf16 v[210:213], v[122:125], v[2:5], 0
	v_max3_f32 v134, v170, v175, v118
	v_mul_f32_e32 v120, 0x3dd53b94, v120
	v_mul_f32_e32 v119, 0x3dd53b94, v121
	v_mfma_f32_16x16x32_bf16 v[210:213], v[176:179], v[6:9], v[210:213]
	v_max3_f32 v134, v134, v120, v119
	v_mfma_f32_16x16x32_bf16 v[210:213], v[180:183], v[10:13], v[210:213]
	v_mfma_f32_16x16x32_bf16 v[210:213], v[184:187], v[14:17], v[210:213]
	v_mfma_f32_16x16x32_bf16 v[210:213], v[188:191], v[18:21], v[210:213]
	v_mfma_f32_16x16x32_bf16 v[122:125], v[122:125], v[26:29], 0
	v_mfma_f32_16x16x32_bf16 v[210:213], v[192:195], v[22:25], v[210:213]
	v_mfma_f32_16x16x32_bf16 v[122:125], v[176:179], v[30:33], v[122:125]
	v_mfma_f32_16x16x32_bf16 v[122:125], v[180:183], v[34:37], v[122:125]
	s_nop 5
	v_mul_f32_e32 v178, 0x3dd53b94, v210
	v_mul_f32_e32 v121, 0x3dd53b94, v211
	v_max3_f32 v134, v134, v178, v121
	v_mul_f32_e32 v180, 0x3dd53b94, v212
	v_mul_f32_e32 v181, 0x3dd53b94, v213
	v_max3_f32 v134, v134, v180, v181
	v_mov_b32_e32 v135, v134
	v_mfma_f32_16x16x32_bf16 v[122:125], v[184:187], v[38:41], v[122:125]
	s_waitcnt lgkmcnt(0)
	s_nop 1
	v_permlane16_swap_b32_e32 v134, v135
	v_max_f32_e32 v134, v134, v135
	v_mov_b32_e32 v135, v134
	v_mfma_f32_16x16x32_bf16 v[122:125], v[188:191], v[42:45], v[122:125]
	s_waitcnt lgkmcnt(0)
	v_mov_b32_e32 v182, v134
	s_nop 1
	v_permlane32_swap_b32_e32 v182, v135
	v_max_f32_e32 v182, v182, v135
	v_sub_f32_e32 v134, v170, v182
	v_exp_f32_e32 v146, v134
	v_mfma_f32_16x16x32_bf16 v[122:125], v[192:195], v[46:49], v[122:125]
	v_cmp_neq_f32_e32 vcc, 1.0, v146
	s_cbranch_vccz .LBB0_1544
	v_mul_f32_e32 v88, v88, v146
	v_mul_f32_e32 v89, v89, v146
	v_mul_f32_e32 v86, v86, v146
	v_mul_f32_e32 v87, v87, v146
	v_mul_f32_e32 v84, v84, v146
	v_mul_f32_e32 v85, v85, v146
	v_mul_f32_e32 v82, v82, v146
	v_mul_f32_e32 v83, v83, v146
	v_mul_f32_e32 v96, v96, v146
	v_mul_f32_e32 v97, v97, v146
	v_mul_f32_e32 v94, v94, v146
	v_mul_f32_e32 v95, v95, v146
	v_mul_f32_e32 v92, v92, v146
	v_mul_f32_e32 v93, v93, v146
	v_mul_f32_e32 v90, v90, v146
	v_mul_f32_e32 v91, v91, v146
	v_mul_f32_e32 v104, v104, v146
	v_mul_f32_e32 v105, v105, v146
	v_mul_f32_e32 v102, v102, v146
	v_mul_f32_e32 v103, v103, v146
	v_mul_f32_e32 v100, v100, v146
	v_mul_f32_e32 v101, v101, v146
	v_mul_f32_e32 v98, v98, v146
	v_mul_f32_e32 v99, v99, v146
	v_mul_f32_e32 v108, v108, v146
	v_mul_f32_e32 v109, v109, v146
	v_mul_f32_e32 v106, v106, v146
	v_mul_f32_e32 v107, v107, v146
	v_mul_f32_e32 v112, v112, v146
	v_mul_f32_e32 v113, v113, v146
	v_mul_f32_e32 v110, v110, v146
	v_mul_f32_e32 v111, v111, v146
.LBB0_1544:
	v_mul_f32_e32 v179, 0x3dd53b94, v114
	v_mul_f32_e32 v176, 0x3dd53b94, v115
	v_max3_f32 v114, v169, v179, v176
	v_mul_f32_e32 v177, 0x3dd53b94, v116
	v_mul_f32_e32 v117, 0x3dd53b94, v117
	v_max3_f32 v114, v114, v177, v117
	v_mul_f32_e32 v170, 0x3dd53b94, v122
	v_mul_f32_e32 v115, 0x3dd53b94, v123
	v_max3_f32 v122, v114, v170, v115
	v_mul_f32_e32 v116, 0x3dd53b94, v124
	v_mul_f32_e32 v114, 0x3dd53b94, v125
	v_max3_f32 v122, v122, v116, v114
	v_mov_b32_e32 v123, v122
	s_waitcnt lgkmcnt(0)
	s_nop 1
	v_permlane16_swap_b32_e32 v122, v123
	v_max_f32_e32 v122, v122, v123
	v_mov_b32_e32 v123, v122
	s_waitcnt lgkmcnt(0)
	v_mov_b32_e32 v183, v122
	s_nop 1
	v_permlane32_swap_b32_e32 v183, v123
	v_max_f32_e32 v183, v183, v123
	v_sub_f32_e32 v122, v169, v183
	v_exp_f32_e32 v122, v122
	s_nop 0
	v_cmp_neq_f32_e32 vcc, 1.0, v122
	s_cbranch_vccz .LBB0_1546
	v_mul_f32_e32 v56, v56, v122
	v_mul_f32_e32 v57, v57, v122
	v_mul_f32_e32 v54, v54, v122
	v_mul_f32_e32 v55, v55, v122
	v_mul_f32_e32 v52, v52, v122
	v_mul_f32_e32 v53, v53, v122
	v_mul_f32_e32 v50, v50, v122
	v_mul_f32_e32 v51, v51, v122
	v_mul_f32_e32 v64, v64, v122
	v_mul_f32_e32 v65, v65, v122
	v_mul_f32_e32 v62, v62, v122
	v_mul_f32_e32 v63, v63, v122
	v_mul_f32_e32 v60, v60, v122
	v_mul_f32_e32 v61, v61, v122
	v_mul_f32_e32 v58, v58, v122
	v_mul_f32_e32 v59, v59, v122
	v_mul_f32_e32 v72, v72, v122
	v_mul_f32_e32 v73, v73, v122
	v_mul_f32_e32 v70, v70, v122
	v_mul_f32_e32 v71, v71, v122
	v_mul_f32_e32 v68, v68, v122
	v_mul_f32_e32 v69, v69, v122
	v_mul_f32_e32 v66, v66, v122
	v_mul_f32_e32 v67, v67, v122
	v_mul_f32_e32 v80, v80, v122
	v_mul_f32_e32 v81, v81, v122
	v_mul_f32_e32 v78, v78, v122
	v_mul_f32_e32 v79, v79, v122
	v_mul_f32_e32 v76, v76, v122
	v_mul_f32_e32 v77, v77, v122
	v_mul_f32_e32 v74, v74, v122
	v_mul_f32_e32 v75, v75, v122
; template <int DKA, int DKB, int DV, bool BAND, bool SINK> ...
;     ...
;       for (int kb2 = 0; kb2 < 2; ++kb2) {
;         const int kb = kk * 2 + kb2;
;         bf16x8 kf[KS];
; #pragma unroll
;         for (int ks = 0; ks < KS; ++ks) {
;           if (ks < KSA) {
;             if (DKA == 128) kf[ks] = *(const bf16x8*)(kst + (kb * 16 + fr) * 256 + (((ks * 4 + fq) ^ fr) * 16));
;             else kf[ks] = *(const bf16x8*)(kst + (kb * 16 + fr) * 128 + (((ks * 4 + fq) ^ swz8) * 16));
;           } else {
;             kf[ks] = *(const bf16x8*)(kst + KASZ + (kb * 16 + fr) * 128 + ((((ks - KSA) * 4 + fq) ^ swz8) * 16));
;           }
;         }
; #pragma unroll
;         for (int qb = 0; qb < 2; ++qb) {
;           f32x4 a = (f32x4){0.f, 0.f, 0.f, 0.f};
; #pragma unroll
;           for (int ks = 0; ks < KS; ++ks) a = mfma16(kf[ks], qf[qb][ks], a);
;           s[qb][kb2] = a;
;         }
;       }
; #pragma unroll
;       for (int qb = 0; qb < 2; ++qb) {
;         float mx = mrun[qb];
;         const int qp = qpos0 + wave * 32 + qb * 16 + fr;
; #pragma unroll
;         for (int kb2 = 0; kb2 < 2; ++kb2)
;     ...
;         float ls = 0.f;
; #pragma unroll
;         for (int kb2 = 0; kb2 < 2; ++kb2)
; #pragma unroll
;           for (int j = 0; j < 4; ++j) {
;             float pv = fexp2(s[qb][kb2][j] - mx);
;             s[qb][kb2][j] = pv;
;             ls += pv;
;           }
;         lrun[qb] = lrun[qb] * alpha + ls;
;         if (__any(alpha != 1.f)) {
; #pragma unroll
;           for (int eb = 0; eb < EB; ++eb) {
;             o[qb][eb][0] *= alpha; o[qb][eb][1] *= alpha; o[qb][eb][2] *= alpha; o[qb][eb][3] *= alpha;
;           }
;         }
;       }
;       bf16x8 pf[2];
; #pragma unroll
;       for (int qb = 0; qb < 2; ++qb)
;         pf[qb] = mk8(pack2(s[qb][0][0], s[qb][0][1]), pack2(s[qb][0][2], s[qb][0][3]),
;                      pack2(s[qb][1][0], s[qb][1][1]), pack2(s[qb][1][2], s[qb][1][3]));
; #pragma unroll
;       for (int eb = 0; eb < EB; ++eb) {
;         const char* vrow = vbuf + (eb * 16 + fr) * 128 + (fq & 1) * 8;
;         uint2 v0 = *(const uint2*)(vrow + (((kk * 4 + (fq >> 1)) ^ swz8) * 16));
;         uint2 v1 = *(const uint2*)(vrow + (((kk * 4 + 2 + (fq >> 1)) ^ swz8) * 16));
;         bf16x8 vf = mk8(v0.x, v0.y, v1.x, v1.y);
; #pragma unroll
;         for (int qb = 0; qb < 2; ++qb) o[qb][eb] = mfma16(vf, pf[qb], o[qb][eb]);
;       }
.LBB0_1546:
	v_sub_f32_e32 v123, v179, v183
	v_exp_f32_e32 v184, v123
	v_sub_f32_e32 v123, v176, v183
	v_sub_f32_e32 v114, v114, v183
	v_exp_f32_e32 v185, v123
	v_sub_f32_e32 v123, v177, v183
	v_exp_f32_e32 v191, v114
	v_sub_f32_e32 v114, v175, v182
	v_exp_f32_e32 v186, v123
	v_lshl_or_b32 v123, s0, 14, v157
	v_exp_f32_e32 v125, v114
	v_sub_f32_e32 v114, v118, v182
	v_exp_f32_e32 v175, v114
	v_sub_f32_e32 v114, v120, v182
	v_add_u32_e32 v124, v123, v164
	v_add_u32_e32 v134, v123, v165
	v_exp_f32_e32 v176, v114
	v_sub_f32_e32 v114, v119, v182
	ds_read2st64_b64 v[192:195], v124 offset0:96 offset1:100
	ds_read2st64_b64 v[210:213], v134 offset0:96 offset1:100
	v_exp_f32_e32 v177, v114
	v_sub_f32_e32 v114, v178, v182
	v_exp_f32_e32 v178, v114
	v_sub_f32_e32 v114, v121, v182
	v_sub_f32_e32 v117, v117, v183
	v_sub_f32_e32 v115, v115, v183
	v_exp_f32_e32 v179, v114
	v_sub_f32_e32 v114, v180, v182
	v_exp_f32_e32 v187, v117
	v_sub_f32_e32 v117, v170, v183
	v_exp_f32_e32 v189, v115
	v_sub_f32_e32 v115, v116, v183
	v_exp_f32_e32 v180, v114
	v_sub_f32_e32 v114, v181, v182
	v_exp_f32_e32 v188, v117
	v_exp_f32_e32 v190, v115
	v_exp_f32_e32 v181, v114
	s_waitcnt lgkmcnt(0)
	v_mov_b32_e32 v216, v210
	v_mov_b32_e32 v217, v211
	v_mov_b32_e32 v210, v194
	v_mov_b32_e32 v211, v195
	v_cvt_pk_bf16_f32 v114, v125, v175
	v_cvt_pk_bf16_f32 v115, v176, v177
	v_cvt_pk_bf16_f32 v116, v178, v179
	v_cvt_pk_bf16_f32 v117, v180, v181
	v_cvt_pk_bf16_f32 v118, v184, v185
	v_cvt_pk_bf16_f32 v119, v186, v187
	v_cvt_pk_bf16_f32 v120, v188, v189
	v_cvt_pk_bf16_f32 v121, v190, v191
	v_mov_b32_e32 v214, v192
	v_mov_b32_e32 v215, v193
	v_mfma_f32_16x16x32_bf16 v[82:85], v[210:213], v[114:117], v[82:85]
	v_mfma_f32_16x16x32_bf16 v[50:53], v[210:213], v[118:121], v[50:53]
	ds_read2st64_b64 v[192:195], v124 offset0:104 offset1:108
	ds_read2st64_b64 v[210:213], v134 offset0:104 offset1:108
	v_mfma_f32_16x16x32_bf16 v[86:89], v[214:217], v[114:117], v[86:89]
	v_mfma_f32_16x16x32_bf16 v[54:57], v[214:217], v[118:121], v[54:57]
	s_waitcnt lgkmcnt(0)
	v_mov_b32_e32 v216, v210
	v_mov_b32_e32 v217, v211
	v_mov_b32_e32 v210, v194
	v_mov_b32_e32 v211, v195
	v_mov_b32_e32 v214, v192
	v_mov_b32_e32 v215, v193
	v_mfma_f32_16x16x32_bf16 v[90:93], v[210:213], v[114:117], v[90:93]
	v_mfma_f32_16x16x32_bf16 v[58:61], v[210:213], v[118:121], v[58:61]
	ds_read2st64_b64 v[192:195], v124 offset0:112 offset1:116
	ds_read2st64_b64 v[210:213], v134 offset0:112 offset1:116
	v_mfma_f32_16x16x32_bf16 v[94:97], v[214:217], v[114:117], v[94:97]
	v_mfma_f32_16x16x32_bf16 v[62:65], v[214:217], v[118:121], v[62:65]
	s_waitcnt lgkmcnt(0)
	v_mov_b32_e32 v216, v210
	v_mov_b32_e32 v217, v211
	v_mov_b32_e32 v210, v194
	v_mov_b32_e32 v211, v195
	v_mov_b32_e32 v214, v192
	v_mov_b32_e32 v215, v193
	v_mfma_f32_16x16x32_bf16 v[98:101], v[210:213], v[114:117], v[98:101]
	v_mfma_f32_16x16x32_bf16 v[66:69], v[210:213], v[118:121], v[66:69]
	ds_read2st64_b64 v[192:195], v124 offset0:120 offset1:124
	ds_read2st64_b64 v[210:213], v134 offset0:120 offset1:124
	v_mfma_f32_16x16x32_bf16 v[102:105], v[214:217], v[114:117], v[102:105]
	v_mfma_f32_16x16x32_bf16 v[70:73], v[214:217], v[118:121], v[70:73]
	s_waitcnt lgkmcnt(0)
	v_mov_b32_e32 v214, v192
	v_mov_b32_e32 v215, v193
	v_mov_b32_e32 v216, v210
	v_mov_b32_e32 v217, v211
	v_mov_b32_e32 v210, v194
	v_mov_b32_e32 v211, v195
	v_mfma_f32_16x16x32_bf16 v[106:109], v[214:217], v[114:117], v[106:109]
	v_mfma_f32_16x16x32_bf16 v[78:81], v[214:217], v[118:121], v[78:81]
	v_mfma_f32_16x16x32_bf16 v[110:113], v[210:213], v[114:117], v[110:113]
	v_mfma_f32_16x16x32_bf16 v[74:77], v[210:213], v[118:121], v[74:77]
	ds_read_b128 v[114:117], v174 offset:8192
	ds_read_b128 v[118:121], v173 offset:8192
	ds_read_b128 v[192:195], v172 offset:8192
	ds_read_b128 v[210:213], v171 offset:8192
	ds_read_b128 v[214:217], v145 offset:20480
	ds_read_b128 v[218:221], v143 offset:20480
	s_waitcnt lgkmcnt(0)
	v_mfma_f32_16x16x32_bf16 v[222:225], v[114:117], v[2:5], 0
	v_mfma_f32_16x16x32_bf16 v[114:117], v[114:117], v[26:29], 0
	v_mfma_f32_16x16x32_bf16 v[222:225], v[118:121], v[6:9], v[222:225]
	v_mfma_f32_16x16x32_bf16 v[114:117], v[118:121], v[30:33], v[114:117]
	v_mfma_f32_16x16x32_bf16 v[222:225], v[192:195], v[10:13], v[222:225]
	v_mfma_f32_16x16x32_bf16 v[114:117], v[192:195], v[34:37], v[114:117]
	v_mfma_f32_16x16x32_bf16 v[222:225], v[210:213], v[14:17], v[222:225]
	v_mfma_f32_16x16x32_bf16 v[114:117], v[210:213], v[38:41], v[114:117]
	v_mfma_f32_16x16x32_bf16 v[222:225], v[214:217], v[18:21], v[222:225]
	v_mfma_f32_16x16x32_bf16 v[114:117], v[214:217], v[42:45], v[114:117]
	v_mfma_f32_16x16x32_bf16 v[222:225], v[218:221], v[22:25], v[222:225]
	v_mfma_f32_16x16x32_bf16 v[114:117], v[218:221], v[46:49], v[114:117]
	ds_read_b128 v[118:121], v174 offset:12288
	ds_read_b128 v[192:195], v173 offset:12288
	ds_read_b128 v[210:213], v172 offset:12288
	ds_read_b128 v[170:173], v171 offset:12288
	ds_read_b128 v[214:217], v145 offset:22528
	ds_read_b128 v[218:221], v143 offset:22528
	s_nop 0
	v_mul_f32_e32 v174, 0x3dd53b94, v224
	s_waitcnt lgkmcnt(0)
	v_mfma_f32_16x16x32_bf16 v[226:229], v[118:121], v[2:5], 0
	v_mfma_f32_16x16x32_bf16 v[226:229], v[192:195], v[6:9], v[226:229]
	v_mfma_f32_16x16x32_bf16 v[226:229], v[210:213], v[10:13], v[226:229]
	v_mfma_f32_16x16x32_bf16 v[118:121], v[118:121], v[26:29], 0
	v_mfma_f32_16x16x32_bf16 v[226:229], v[170:173], v[14:17], v[226:229]
	v_mfma_f32_16x16x32_bf16 v[118:121], v[192:195], v[30:33], v[118:121]
	v_mul_f32_e32 v193, 0x3dd53b94, v222
	v_mul_f32_e32 v192, 0x3dd53b94, v223
	v_max3_f32 v124, v182, v193, v192
	v_mfma_f32_16x16x32_bf16 v[226:229], v[214:217], v[18:21], v[226:229]
	v_mfma_f32_16x16x32_bf16 v[118:121], v[210:213], v[34:37], v[118:121]
	v_mfma_f32_16x16x32_bf16 v[226:229], v[218:221], v[22:25], v[226:229]
	v_mfma_f32_16x16x32_bf16 v[118:121], v[170:173], v[38:41], v[118:121]
	v_mul_f32_e32 v173, 0x3dd53b94, v225
	v_max3_f32 v124, v124, v174, v173
	s_nop 4
	v_mul_f32_e32 v172, 0x3dd53b94, v226
	v_mul_f32_e32 v171, 0x3dd53b94, v227
	v_max3_f32 v124, v124, v172, v171
	v_mul_f32_e32 v145, 0x3dd53b94, v228
	v_mul_f32_e32 v143, 0x3dd53b94, v229
	v_max3_f32 v124, v124, v145, v143
	v_mov_b32_e32 v134, v124
	v_mfma_f32_16x16x32_bf16 v[118:121], v[214:217], v[42:45], v[118:121]
	s_waitcnt lgkmcnt(0)
	s_nop 1
	v_permlane16_swap_b32_e32 v124, v134
	v_max_f32_e32 v124, v124, v134
	v_mov_b32_e32 v134, v124
	v_mfma_f32_16x16x32_bf16 v[118:121], v[218:221], v[46:49], v[118:121]
	s_waitcnt lgkmcnt(0)
	v_mov_b32_e32 v170, v124
	s_nop 1
	v_permlane32_swap_b32_e32 v170, v134
	v_max_f32_e32 v170, v170, v134
	v_sub_f32_e32 v124, v182, v170
	v_exp_f32_e32 v124, v124
	s_nop 0
	v_cmp_neq_f32_e32 vcc, 1.0, v124
	s_cbranch_vccz .LBB0_1548
; template <int DKA, int DKB, int DV, bool BAND, bool SINK> ...
;     ...
;         lrun[qb] = lrun[qb] * alpha + ls;
;         if (__any(alpha != 1.f)) {
; #pragma unroll
;           for (int eb = 0; eb < EB; ++eb) {
;             o[qb][eb][0] *= alpha; o[qb][eb][1] *= alpha; o[qb][eb][2] *= alpha; o[qb][eb][3] *= alpha;
;           }
;         }
	v_mul_f32_e32 v88, v88, v124
	v_mul_f32_e32 v89, v89, v124
	v_mul_f32_e32 v86, v86, v124
	v_mul_f32_e32 v87, v87, v124
	v_mul_f32_e32 v84, v84, v124
	v_mul_f32_e32 v85, v85, v124
	v_mul_f32_e32 v82, v82, v124
	v_mul_f32_e32 v83, v83, v124
	v_mul_f32_e32 v96, v96, v124
	v_mul_f32_e32 v97, v97, v124
	v_mul_f32_e32 v94, v94, v124
	v_mul_f32_e32 v95, v95, v124
	v_mul_f32_e32 v92, v92, v124
	v_mul_f32_e32 v93, v93, v124
	v_mul_f32_e32 v90, v90, v124
	v_mul_f32_e32 v91, v91, v124
	v_mul_f32_e32 v104, v104, v124
	v_mul_f32_e32 v105, v105, v124
	v_mul_f32_e32 v102, v102, v124
	v_mul_f32_e32 v103, v103, v124
	v_mul_f32_e32 v100, v100, v124
	v_mul_f32_e32 v101, v101, v124
	v_mul_f32_e32 v98, v98, v124
	v_mul_f32_e32 v99, v99, v124
	v_mul_f32_e32 v108, v108, v124
	v_mul_f32_e32 v109, v109, v124
	v_mul_f32_e32 v106, v106, v124
	v_mul_f32_e32 v107, v107, v124
	v_mul_f32_e32 v112, v112, v124
	v_mul_f32_e32 v113, v113, v124
	v_mul_f32_e32 v110, v110, v124
	v_mul_f32_e32 v111, v111, v124
.LBB0_1548:
	v_mul_f32_e32 v210, 0x3dd53b94, v114
	v_mul_f32_e32 v195, 0x3dd53b94, v115
	v_max3_f32 v114, v183, v210, v195
	v_mul_f32_e32 v194, 0x3dd53b94, v116
	v_mul_f32_e32 v182, 0x3dd53b94, v117
	v_max3_f32 v114, v114, v194, v182
	v_mul_f32_e32 v118, 0x3dd53b94, v118
	v_mul_f32_e32 v117, 0x3dd53b94, v119
	v_max3_f32 v114, v114, v118, v117
	v_mul_f32_e32 v116, 0x3dd53b94, v120
	v_mul_f32_e32 v115, 0x3dd53b94, v121
	v_max3_f32 v114, v114, v116, v115
	v_mov_b32_e32 v119, v114
	s_waitcnt lgkmcnt(0)
	s_nop 1
	v_permlane16_swap_b32_e32 v114, v119
	v_max_f32_e32 v114, v114, v119
	v_mov_b32_e32 v119, v114
	s_waitcnt lgkmcnt(0)
	v_mov_b32_e32 v169, v114
	s_nop 1
	v_permlane32_swap_b32_e32 v169, v119
	v_max_f32_e32 v169, v169, v119
	v_sub_f32_e32 v114, v183, v169
	v_exp_f32_e32 v114, v114
	s_nop 0
	v_cmp_neq_f32_e32 vcc, 1.0, v114
	s_cbranch_vccz .LBB0_1550
	v_mul_f32_e32 v56, v56, v114
	v_mul_f32_e32 v57, v57, v114
	v_mul_f32_e32 v54, v54, v114
	v_mul_f32_e32 v55, v55, v114
	v_mul_f32_e32 v52, v52, v114
	v_mul_f32_e32 v53, v53, v114
	v_mul_f32_e32 v50, v50, v114
	v_mul_f32_e32 v51, v51, v114
	v_mul_f32_e32 v64, v64, v114
	v_mul_f32_e32 v65, v65, v114
	v_mul_f32_e32 v62, v62, v114
	v_mul_f32_e32 v63, v63, v114
	v_mul_f32_e32 v60, v60, v114
	v_mul_f32_e32 v61, v61, v114
	v_mul_f32_e32 v58, v58, v114
	v_mul_f32_e32 v59, v59, v114
	v_mul_f32_e32 v72, v72, v114
	v_mul_f32_e32 v73, v73, v114
	v_mul_f32_e32 v70, v70, v114
	v_mul_f32_e32 v71, v71, v114
	v_mul_f32_e32 v68, v68, v114
	v_mul_f32_e32 v69, v69, v114
	v_mul_f32_e32 v66, v66, v114
	v_mul_f32_e32 v67, v67, v114
	v_mul_f32_e32 v80, v80, v114
	v_mul_f32_e32 v81, v81, v114
	v_mul_f32_e32 v78, v78, v114
	v_mul_f32_e32 v79, v79, v114
	v_mul_f32_e32 v76, v76, v114
	v_mul_f32_e32 v77, v77, v114
	v_mul_f32_e32 v74, v74, v114
	v_mul_f32_e32 v75, v75, v114
